# attention: direct per-wave bias table + XCD-local work queues (each XCD takes one batch so K/V stays in its L2)
# speedup vs baseline: 1.1307x; 1.0224x over previous
;   unsigned char* blut = (unsigned char*)lds; float* tbl = (float*)(lds + 4096);
;   build_lut(blut, tbl, p.in[I_RELB]);
;   unsigned* ctr = (unsigned*)(p.ws + OFF_MISC) + layer * 2 + 1 + rep * 8;
;   for (;;) {
;     const int item = wave_fetch(ctr);
;     if (item >= 128 * 48) break;
.LBB0_700:
	s_or_b64 exec, exec, s[8:9]
	v_readlane_b32 s10, v254, 1
	s_and_b32 s10, s10, 7
	s_mul_i32 s101, s10, 6
	s_lshl_b32 s10, s10, 2
	s_lshl_b32 s11, s47, 5
	s_add_u32 s10, s10, s11
	s_add_u32 s10, s10, 0x65c0080
	s_add_u32 s10, s34, s10
	s_addc_u32 s11, s35, 0
	s_mov_b64 s[54:55], 0
	s_waitcnt vmcnt(0) lgkmcnt(0)
	s_barrier
	s_branch .LBB0_703

; #define TIDX get_tid_()
; DI float bf2f(bf16_t b) { return __uint_as_float(((unsigned)b) << 16); }
; DI int crow(int i, int h) { return (i & 3) + 8 * (i >> 2) + 4 * h; }
; DI void nsa_main_item(const Params& p, int b, int head, int qb, const unsigned char* blut, const float* tbl) {
;   const int lane = TIDX & 63, r = lane & 31, h = lane >> 5;
;   const int g = head / 3, bg = b * 2 + g;
;   const int t = qb * 32 + r;
;   const float* tblh = tbl + head * 32;
;   bf16x8 qf[4];
;   load_q(qf, (const bf16_t*)(p.ws + OFF_QN) + (size_t)(b * 4096 + t) * 384 + head * 64 + 8 * h);
;   const unsigned long long selm = ((const unsigned long long*)(p.ws + OFF_SELM))[(size_t)bg * 4096 + t];
;   const float* gates = (const float*)(p.ws + OFF_GATES) + (size_t)(b * 4096 + t) * 18 + head * 3;
;   const float g1 = gates[1];
;   f32x16 y0, y1;
;   {
;     const bf16_t* oc = (const bf16_t*)(p.ws + OFF_OC) + (size_t)(b * 4096 + t) * 384 + head * 64;
;     const bf16_t* yw = (const bf16_t*)(p.ws + OFF_Y) + (size_t)(b * 4096 + t) * 768 + head * 64;
; #pragma unroll
;     for (int i = 0; i < 16; ++i) { y0[i] = bf2f(oc[crow(i, h)]) + bf2f(yw[crow(i, h)]); y1[i] = bf2f(oc[32 + crow(i, h)]) + bf2f(yw[32 + crow(i, h)]); }
;   }
;   {
;     const bf16_t* K = (const bf16_t*)(p.ws + OFF_KSEL) + (size_t)bg * 4096 * 64;
;     const bf16_t* Vt = (const bf16_t*)(p.ws + OFF_VSELT) + (size_t)bg * 64 * 4096;
;     AttnSt st; attn_init(st);
;     ...
;   for (;;) {
;     const int item = wave_fetch(ctr);
;     if (item >= 128 * 48) break;
;     const int qb = 127 - item / 48, sub = item % 48;
;     nsa_main_item(p, sub / 6, sub % 6, qb, blut, tbl);
.LBB0_707:
	s_or_b64 exec, exec, s[8:9]
	v_lshlrev_b32_e32 v1, 2, v188
	v_and_b32_e32 v1, 0x100, v1
	ds_bpermute_b32 v0, v1, v0
	s_movk_i32 s8, 0x300
	s_waitcnt lgkmcnt(0)
	v_cmp_gt_i32_e32 vcc, s8, v0
	s_mov_b64 s[8:9], -1
	s_and_saveexec_b64 s[14:15], vcc
	s_cbranch_execz .LBB0_702
	v_mul_u32_u24_e32 v1, 0xaaab, v0
	v_lshrrev_b32_e32 v1, 18, v1
	v_mul_u32_u24_e32 v1, 42, v1
	v_add3_u32 v0, v0, v1, s101
	s_mov_b32 s8, 0xd5555555
	v_mul_hi_i32 v1, v0, s8
	v_lshrrev_b32_e32 v2, 31, v1
	v_ashrrev_i32_e32 v1, 3, v1
	s_movk_i32 s8, 0x7f
	v_add3_u32 v217, v1, v2, s8
	s_mov_b32 s8, 0x2aaaaaab
	v_mul_hi_i32 v1, v0, s8
	v_lshrrev_b32_e32 v2, 31, v1
	v_lshrrev_b32_e32 v1, 3, v1
	v_add_u32_e32 v1, v1, v2
	v_mul_lo_u32 v1, v1, 48
	v_sub_u32_e32 v0, v0, v1
	v_mul_lo_u16_e32 v1, 43, v0
	v_lshrrev_b16_e32 v2, 15, v1
	v_add_u16_sdwa v1, v1, v2 dst_sel:DWORD dst_unused:UNUSED_PAD src0_sel:BYTE_1 src1_sel:DWORD
	v_bfe_i32 v2, v1, 0, 8
	v_mul_lo_u16_e32 v1, 6, v1
	v_sub_u16_e32 v0, v0, v1
	v_bfe_i32 v28, v0, 0, 8
	v_mov_b32_e32 v0, v129
	v_lshlrev_b32_e32 v31, 5, v217
	v_and_b32_e32 v29, 31, v0
	v_bfe_u32 v30, v0, 5, 1
	v_mul_lo_u16_e32 v0, 0x56, v28
	v_lshrrev_b16_e32 v1, 15, v0
	v_add_u16_sdwa v0, v0, v1 dst_sel:DWORD dst_unused:UNUSED_PAD src0_sel:BYTE_1 src1_sel:DWORD
	v_readlane_b32 s8, v253, 13
	v_bfe_i32 v0, v0, 0, 8
	v_or_b32_e32 v10, v29, v31
	v_readlane_b32 s9, v253, 14
	v_lshl_add_u32 v8, v2, 1, v0
	v_lshl_add_u32 v22, v2, 12, v10
	v_mov_b64_e32 v[0:1], s[8:9]
	s_movk_i32 s23, 0x300
	v_mad_i64_i32 v[0:1], s[8:9], v22, s23, v[0:1]
	v_lshlrev_b32_e32 v2, 6, v28
	v_ashrrev_i32_e32 v3, 31, v2
	v_readlane_b32 s8, v253, 23
	v_lshlrev_b64 v[2:3], 1, v[2:3]
	v_readlane_b32 s9, v253, 24
	v_lshl_add_u64 v[4:5], v[0:1], 0, v[2:3]
	v_lshlrev_b32_e32 v130, 3, v30
	v_mov_b64_e32 v[0:1], s[8:9]
	v_mad_i64_i32 v[0:1], s[8:9], v22, s23, v[0:1]
	v_readlane_b32 s8, v253, 19
	v_readlane_b32 s9, v253, 20
	v_lshl_add_u64 v[0:1], v[0:1], 0, v[2:3]
	v_ashrrev_i32_e32 v9, 31, v8
	v_mov_b64_e32 v[6:7], s[8:9]
	s_movk_i32 s8, 0x600
	v_mad_i64_i32 v[6:7], s[8:9], v22, s8, v[6:7]
	v_lshl_add_u64 v[2:3], v[6:7], 0, v[2:3]
	v_lshl_add_u64 v[12:13], v[0:1], 0, v[130:131]
	v_readlane_b32 s8, v253, 25
	v_lshlrev_b32_e32 v0, 3, v29
	v_lshl_add_u64 v[132:133], v[2:3], 0, v[130:131]
	v_lshlrev_b64 v[14:15], 19, v[8:9]
	v_readlane_b32 s9, v253, 26
	v_lshl_or_b32 v130, v30, 8, v0
	v_lshlrev_b32_e32 v20, 1, v130
	v_lshl_add_u64 v[16:17], s[8:9], 0, v[14:15]
	v_mov_b32_e32 v21, v131
	v_lshl_add_u64 v[148:149], v[16:17], 0, v[20:21]
	global_load_dwordx4 v[0:3], v[148:149], off
	v_lshlrev_b32_e32 v6, 4, v30
	v_mov_b32_e32 v7, v131
	v_lshl_add_u64 v[4:5], v[4:5], 0, v[6:7]
	global_load_dwordx4 v[80:83], v[4:5], off
	v_mov_b64_e32 v[6:7], s[34:35]
	s_movk_i32 s8, 0x48
	v_mad_i64_i32 v[6:7], s[8:9], v22, s8, v[6:7]
	v_mul_i32_i24_e32 v22, 3, v28
	v_ashrrev_i32_e32 v23, 31, v22
	v_cmp_eq_u32_e32 vcc, 0, v217
	v_lshl_add_u64 v[6:7], v[22:23], 2, v[6:7]
	s_mov_b32 s8, 0x165c4000
	v_cndmask_b32_e64 v18, v197, 0, vcc
	v_add_co_u32_e32 v22, vcc, s8, v6
	v_readlane_b32 s8, v253, 21
	s_nop 0
	v_addc_co_u32_e32 v23, vcc, 0, v7, vcc
	global_load_dwordx4 v[84:87], v[4:5], off offset:32
	global_load_dwordx4 v[88:91], v[4:5], off offset:64
	global_load_dwordx4 v[92:95], v[4:5], off offset:96
	global_load_dwordx2 v[136:137], v[12:13], off offset:64
	global_load_dwordx2 v[144:145], v[12:13], off offset:80
	global_load_dwordx2 v[150:151], v[12:13], off offset:32
	global_load_dwordx2 v[160:161], v[12:13], off offset:48
	global_load_dwordx2 v[134:135], v[132:133], off
	global_load_dwordx2 v[142:143], v[132:133], off offset:16
	global_load_dwordx2 v[152:153], v[132:133], off offset:32
	global_load_dwordx2 v[162:163], v[132:133], off offset:48
	global_load_dwordx2 v[154:155], v[12:13], off offset:96
	global_load_dwordx2 v[164:165], v[12:13], off offset:112
	global_load_dwordx4 v[4:7], v[148:149], off offset:1024
	global_load_dwordx2 v[138:139], v[132:133], off offset:64
	global_load_dwordx2 v[146:147], v[132:133], off offset:80
	global_load_dwordx2 v[158:159], v[132:133], off offset:96
	global_load_dwordx2 v[166:167], v[132:133], off offset:112
	v_lshlrev_b64 v[8:9], 15, v[8:9]
	v_readlane_b32 s9, v253, 22
	v_mov_b32_e32 v11, v131
	v_mov_b32_e32 v19, v131
	v_lshl_add_u64 v[8:9], s[8:9], 0, v[8:9]
	v_lshl_add_u64 v[24:25], v[10:11], 3, v[8:9]
	v_lshl_add_u64 v[26:27], v[16:17], 0, v[18:19]
	global_load_dwordx4 v[8:11], v[148:149], off offset:2048
	global_load_dwordx2 v[168:169], v[24:25], off
	global_load_dword v218, v[22:23], off offset:4
	global_load_dwordx2 v[140:141], v[12:13], off
	global_load_dwordx2 v[156:157], v[12:13], off offset:16
	global_load_dwordx4 v[16:19], v[148:149], off offset:3072
	v_readlane_b32 s8, v253, 27
	v_readlane_b32 s9, v253, 28
	v_lshl_add_u64 v[12:13], v[26:27], 0, v[20:21]
	global_load_dwordx4 v[108:111], v[12:13], off offset:3072
	global_load_dwordx4 v[104:107], v[12:13], off offset:2048
	global_load_dwordx4 v[100:103], v[12:13], off offset:1024
	global_load_dwordx4 v[96:99], v[12:13], off
	v_lshl_add_u64 v[14:15], s[8:9], 0, v[14:15]
	v_lshl_add_u64 v[170:171], v[14:15], 0, v[130:131]
	global_load_dwordx2 v[114:115], v[170:171], off offset:3584
	global_load_dwordx2 v[112:113], v[170:171], off offset:3072
	global_load_dwordx2 v[118:119], v[170:171], off offset:2560
	global_load_dwordx2 v[116:117], v[170:171], off offset:2048
	global_load_dwordx2 v[122:123], v[170:171], off offset:1536
	global_load_dwordx2 v[120:121], v[170:171], off offset:1024
	global_load_dwordx2 v[126:127], v[170:171], off offset:512
	global_load_dwordx2 v[124:125], v[170:171], off
	s_mov_b32 s56, 0
	s_mov_b32 s57, s56
	s_mov_b32 s58, s56
	s_mov_b32 s59, s56
	s_mov_b32 s60, s56
	s_mov_b32 s61, s56
	s_mov_b32 s62, s56
	s_mov_b32 s63, s56
	s_mov_b32 s64, s56
	s_mov_b32 s65, s56
	s_mov_b32 s66, s56
	s_mov_b32 s67, s56
	s_mov_b32 s68, s56
	s_mov_b32 s69, s56
	s_waitcnt vmcnt(36)
; #define MFMA32(a, b, c) __builtin_amdgcn_mfma_f32_32x32x16_bf16((a), (b), (c), 0, 0, 0)
; template <class KP, class VP, class ACT, class FILL>
; DI void attn_loop(AttnSt& st, const bf16x8 (&qf)[4], int k0, int k1, size_t vstride, KP kp, VP vp, ACT act, FILL fill) {
;   KVT cur, nxt;
;   {
;     KVT t0; load_kv(t0, kp(k0), vp(k0), vstride);
; #pragma unroll
;     for (int i = 0; i < 8; ++i) cur.v[i] = t0.v[i];
; #pragma unroll
;     for (int i = 0; i < 4; ++i) cur.k[i] = t0.k[i];
;   }
;   f32x16 s_cur;
;   { const float z = 0.f;
; #pragma unroll
;     for (int i = 0; i < 16; ++i) s_cur[i] = z; }
; #pragma unroll
;   for (int ss = 0; ss < 4; ++ss) s_cur = MFMA32(cur.k[ss], qf[ss], s_cur);
;   {
;     const int kn = (k0 < k1) ? k0 + 1 : k1;
;     const bf16_t* krow = kp(kn);
; #pragma unroll
;     for (int ss = 0; ss < 4; ++ss) nxt.k[ss] = *(const bf16x8*)(krow + 512 * ss);
;   }
; DI void bias16(const unsigned char* blut, const float* tblh, const int (&dist)[16], float (&bv)[16]) {
;   int bk[16];
; #pragma unroll
;   for (int i = 0; i < 16; ++i) { const int d = dist[i] < 0 ? 0 : (dist[i] > 2048 ? 2048 : dist[i]); bk[i] = blut[d]; }
; #pragma unroll
;   for (int i = 0; i < 16; ++i) asm volatile("" : "+v"(bk[i]));
; #pragma unroll
;   for (int i = 0; i < 16; ++i) bv[i] = tblh[bk[i]];
; #pragma unroll
;   for (int i = 0; i < 16; ++i) asm volatile("" : "+v"(bv[i]));
; }
	v_mfma_f32_32x32x16_bf16 v[48:63], v[0:3], v[80:83], 0
	s_mov_b32 s70, s56
	s_mov_b32 s71, s56
	v_lshlrev_b32_e32 v20, 2, v30
	v_lshl_add_u32 v219, v28, 7, 0
	v_subrev_u32_e32 v220, 31, v31
	v_sub_u32_e32 v221, v29, v20
	v_mov_b32_e32 v222, 0
	s_waitcnt vmcnt(22)
	v_mfma_f32_32x32x16_bf16 v[48:63], v[4:7], v[84:87], v[48:63]
	v_mov_b32_e32 v223, 0xff800000
	s_waitcnt vmcnt(17)
	v_mfma_f32_32x32x16_bf16 v[48:63], v[8:11], v[88:91], v[48:63]
	v_mov_b64_e32 v[0:1], s[56:57]
	v_mov_b64_e32 v[14:15], s[70:71]
	v_mov_b64_e32 v[2:3], s[58:59]
	v_mov_b64_e32 v[4:5], s[60:61]
	v_mov_b64_e32 v[6:7], s[62:63]
	v_mov_b64_e32 v[8:9], s[64:65]
	v_mov_b64_e32 v[10:11], s[66:67]
	s_waitcnt vmcnt(12)
	v_mfma_f32_32x32x16_bf16 v[48:63], v[16:19], v[92:95], v[48:63]
	v_mov_b64_e32 v[12:13], s[68:69]
	v_mov_b64_e32 v[30:31], v[14:15]
	s_mov_b64 s[58:59], 0
	v_mov_b64_e32 v[28:29], v[12:13]
	v_mov_b64_e32 v[26:27], v[10:11]
	v_mov_b64_e32 v[24:25], v[8:9]
	v_mov_b64_e32 v[22:23], v[6:7]
	v_mov_b64_e32 v[20:21], v[4:5]
	v_mov_b64_e32 v[18:19], v[2:3]
	v_mov_b64_e32 v[16:17], v[0:1]
	s_waitcnt vmcnt(0)
	v_readfirstlane_b32 s60, v217
	s_mov_b32 s56, 0
	s_mov_b32 s23, 0
	s_min_u32 s24, s23, s60
	s_lshl_b32 s26, s24, 12
	s_mov_b32 s27, 0
	v_lshl_add_u64 v[248:249], v[148:149], 0, s[26:27]
	global_load_dwordx4 v[96:99], v[248:249], off
	global_load_dwordx4 v[100:103], v[248:249], off offset:1024
	global_load_dwordx4 v[104:107], v[248:249], off offset:2048
	global_load_dwordx4 v[108:111], v[248:249], off offset:3072
	s_mov_b32 s23, 1
	s_min_u32 s24, s23, s60
	s_lshl_b32 s26, s24, 12
	s_mov_b32 s27, 0
	v_lshl_add_u64 v[248:249], v[148:149], 0, s[26:27]
	global_load_dwordx4 v[112:115], v[248:249], off
	global_load_dwordx4 v[116:119], v[248:249], off offset:1024
	global_load_dwordx4 v[120:123], v[248:249], off offset:2048
	global_load_dwordx4 v[124:127], v[248:249], off offset:3072
	s_mov_b32 s23, 0
	s_min_u32 s24, s23, s60
	s_lshl_b32 s26, s24, 12
	s_mov_b32 s27, 0
	v_lshl_add_u64 v[250:251], v[170:171], 0, s[26:27]
	global_load_dwordx2 v[64:65], v[250:251], off
	global_load_dwordx2 v[66:67], v[250:251], off offset:512
	global_load_dwordx2 v[68:69], v[250:251], off offset:1024
	global_load_dwordx2 v[70:71], v[250:251], off offset:1536
	global_load_dwordx2 v[72:73], v[250:251], off offset:2048
	global_load_dwordx2 v[74:75], v[250:251], off offset:2560
	global_load_dwordx2 v[76:77], v[250:251], off offset:3072
	global_load_dwordx2 v[78:79], v[250:251], off offset:3584
	s_mov_b32 s23, 1
	s_min_u32 s24, s23, s60
	s_lshl_b32 s26, s24, 12
	s_mov_b32 s27, 0
	v_lshl_add_u64 v[250:251], v[170:171], 0, s[26:27]
	global_load_dwordx2 v[172:173], v[250:251], off
	global_load_dwordx2 v[174:175], v[250:251], off offset:512
	global_load_dwordx2 v[176:177], v[250:251], off offset:1024
	global_load_dwordx2 v[178:179], v[250:251], off offset:1536
	global_load_dwordx2 v[180:181], v[250:251], off offset:2048
	global_load_dwordx2 v[182:183], v[250:251], off offset:2560
	global_load_dwordx2 v[184:185], v[250:251], off offset:3072
	global_load_dwordx2 v[186:187], v[250:251], off offset:3584
	v_lshrrev_b32_e32 v246, 6, v129
	v_mul_u32_u24_e32 v246, 6912, v246
	v_add_u32_e32 v242, 8192, v246
	v_and_b32_e32 v246, 63, v129
	v_add_u32_e32 v224, -64, v246
	v_mov_b32_e32 v224, 0
	v_mov_b32_e32 v225, v246
	v_add_u32_e32 v226, 64, v246
	v_add_u32_e32 v227, 128, v246
	v_add_u32_e32 v228, 192, v246
	v_add_u32_e32 v229, 256, v246
	v_add_u32_e32 v230, 320, v246
	v_add_u32_e32 v231, 384, v246
	v_add_u32_e32 v232, 448, v246
	ds_read_u8 v224, v224
	ds_read_u8 v225, v225
	ds_read_u8 v226, v226
	ds_read_u8 v227, v227
	ds_read_u8 v228, v228
	ds_read_u8 v229, v229
	ds_read_u8 v230, v230
	ds_read_u8 v231, v231
	ds_read_u8 v232, v232
	s_waitcnt lgkmcnt(8)
	v_lshl_add_u32 v224, v224, 2, v219
	s_waitcnt lgkmcnt(7)
	v_lshl_add_u32 v225, v225, 2, v219
	s_waitcnt lgkmcnt(6)
	v_lshl_add_u32 v226, v226, 2, v219
	s_waitcnt lgkmcnt(5)
	v_lshl_add_u32 v227, v227, 2, v219
	s_waitcnt lgkmcnt(4)
	v_lshl_add_u32 v228, v228, 2, v219
	s_waitcnt lgkmcnt(3)
	v_lshl_add_u32 v229, v229, 2, v219
	s_waitcnt lgkmcnt(2)
	v_lshl_add_u32 v230, v230, 2, v219
	s_waitcnt lgkmcnt(1)
	v_lshl_add_u32 v231, v231, 2, v219
	s_waitcnt lgkmcnt(0)
	v_lshl_add_u32 v232, v232, 2, v219
	ds_read_b32 v224, v224 offset:4096
	ds_read_b32 v225, v225 offset:4096
	ds_read_b32 v226, v226 offset:4096
	ds_read_b32 v227, v227 offset:4096
	ds_read_b32 v228, v228 offset:4096
	ds_read_b32 v229, v229 offset:4096
	ds_read_b32 v230, v230 offset:4096
	ds_read_b32 v231, v231 offset:4096
	ds_read_b32 v232, v232 offset:4096
	v_lshl_add_u32 v244, v246, 2, v242
	s_waitcnt lgkmcnt(8)
	ds_write_b32 v244, v224 offset:0
	s_waitcnt lgkmcnt(7)
	ds_write_b32 v244, v225 offset:256
	s_waitcnt lgkmcnt(6)
	ds_write_b32 v244, v226 offset:512
	s_waitcnt lgkmcnt(5)
	ds_write_b32 v244, v227 offset:768
	s_waitcnt lgkmcnt(4)
	ds_write_b32 v244, v228 offset:1024
	s_waitcnt lgkmcnt(3)
	ds_write_b32 v244, v229 offset:1280
	s_waitcnt lgkmcnt(2)
	ds_write_b32 v244, v230 offset:1536
	s_waitcnt lgkmcnt(1)
	ds_write_b32 v244, v231 offset:1792
	s_waitcnt lgkmcnt(0)
	ds_write_b32 v244, v232 offset:2048
	v_add_u32_e32 v224, 512, v246
	v_add_u32_e32 v225, 576, v246
	v_add_u32_e32 v226, 640, v246
	v_add_u32_e32 v227, 704, v246
	v_add_u32_e32 v228, 768, v246
	v_add_u32_e32 v229, 832, v246
	v_add_u32_e32 v230, 896, v246
	v_add_u32_e32 v231, 960, v246
	v_add_u32_e32 v232, 1024, v246
	ds_read_u8 v224, v224
	ds_read_u8 v225, v225
	ds_read_u8 v226, v226
	ds_read_u8 v227, v227
	ds_read_u8 v228, v228
	ds_read_u8 v229, v229
	ds_read_u8 v230, v230
	ds_read_u8 v231, v231
	ds_read_u8 v232, v232
	s_waitcnt lgkmcnt(8)
; DI void bias16(const unsigned char* blut, const float* tblh, const int (&dist)[16], float (&bv)[16]) {
;   int bk[16];
; #pragma unroll
;   for (int i = 0; i < 16; ++i) { const int d = dist[i] < 0 ? 0 : (dist[i] > 2048 ? 2048 : dist[i]); bk[i] = blut[d]; }
; #pragma unroll
;   for (int i = 0; i < 16; ++i) asm volatile("" : "+v"(bk[i]));
; #pragma unroll
;   for (int i = 0; i < 16; ++i) bv[i] = tblh[bk[i]];
; #pragma unroll
;   for (int i = 0; i < 16; ++i) asm volatile("" : "+v"(bv[i]));
; }
; DI void nsa_main_item(const Params& p, int b, int head, int qb, const unsigned char* blut, const float* tbl) {
;     ...
;           const float b31 = tblh[31];
	v_lshl_add_u32 v224, v224, 2, v219
	s_waitcnt lgkmcnt(7)
	v_lshl_add_u32 v225, v225, 2, v219
	s_waitcnt lgkmcnt(6)
	v_lshl_add_u32 v226, v226, 2, v219
	s_waitcnt lgkmcnt(5)
	v_lshl_add_u32 v227, v227, 2, v219
	s_waitcnt lgkmcnt(4)
	v_lshl_add_u32 v228, v228, 2, v219
	s_waitcnt lgkmcnt(3)
	v_lshl_add_u32 v229, v229, 2, v219
	s_waitcnt lgkmcnt(2)
	v_lshl_add_u32 v230, v230, 2, v219
	s_waitcnt lgkmcnt(1)
	v_lshl_add_u32 v231, v231, 2, v219
	s_waitcnt lgkmcnt(0)
	v_lshl_add_u32 v232, v232, 2, v219
	ds_read_b32 v224, v224 offset:4096
	ds_read_b32 v225, v225 offset:4096
	ds_read_b32 v226, v226 offset:4096
	ds_read_b32 v227, v227 offset:4096
	ds_read_b32 v228, v228 offset:4096
	ds_read_b32 v229, v229 offset:4096
	ds_read_b32 v230, v230 offset:4096
	ds_read_b32 v231, v231 offset:4096
	ds_read_b32 v232, v232 offset:4096
	v_lshl_add_u32 v244, v246, 2, v242
	s_waitcnt lgkmcnt(8)
	ds_write_b32 v244, v224 offset:2304
	s_waitcnt lgkmcnt(7)
	ds_write_b32 v244, v225 offset:2560
	s_waitcnt lgkmcnt(6)
	ds_write_b32 v244, v226 offset:2816
	s_waitcnt lgkmcnt(5)
	ds_write_b32 v244, v227 offset:3072
	s_waitcnt lgkmcnt(4)
	ds_write_b32 v244, v228 offset:3328
	s_waitcnt lgkmcnt(3)
	ds_write_b32 v244, v229 offset:3584
	s_waitcnt lgkmcnt(2)
	ds_write_b32 v244, v230 offset:3840
	s_waitcnt lgkmcnt(1)
	ds_write_b32 v244, v231 offset:4096
	s_waitcnt lgkmcnt(0)
	ds_write_b32 v244, v232 offset:4352
	v_add_u32_e32 v224, 1088, v246
	v_add_u32_e32 v225, 1152, v246
	v_add_u32_e32 v226, 1216, v246
	v_add_u32_e32 v227, 1280, v246
	v_add_u32_e32 v228, 1344, v246
	v_add_u32_e32 v229, 1408, v246
	v_add_u32_e32 v230, 1472, v246
	v_add_u32_e32 v231, 1536, v246
	v_add_u32_e32 v232, 1600, v246
	ds_read_u8 v224, v224
	ds_read_u8 v225, v225
	ds_read_u8 v226, v226
	ds_read_u8 v227, v227
	ds_read_u8 v228, v228
	ds_read_u8 v229, v229
	ds_read_u8 v230, v230
	ds_read_u8 v231, v231
	ds_read_u8 v232, v232
	s_waitcnt lgkmcnt(8)
	v_lshl_add_u32 v224, v224, 2, v219
	s_waitcnt lgkmcnt(7)
	v_lshl_add_u32 v225, v225, 2, v219
	s_waitcnt lgkmcnt(6)
	v_lshl_add_u32 v226, v226, 2, v219
	s_waitcnt lgkmcnt(5)
	v_lshl_add_u32 v227, v227, 2, v219
	s_waitcnt lgkmcnt(4)
	v_lshl_add_u32 v228, v228, 2, v219
	s_waitcnt lgkmcnt(3)
	v_lshl_add_u32 v229, v229, 2, v219
	s_waitcnt lgkmcnt(2)
	v_lshl_add_u32 v230, v230, 2, v219
	s_waitcnt lgkmcnt(1)
	v_lshl_add_u32 v231, v231, 2, v219
	s_waitcnt lgkmcnt(0)
	v_lshl_add_u32 v232, v232, 2, v219
	ds_read_b32 v224, v224 offset:4096
	ds_read_b32 v225, v225 offset:4096
	ds_read_b32 v226, v226 offset:4096
	ds_read_b32 v227, v227 offset:4096
	ds_read_b32 v228, v228 offset:4096
	ds_read_b32 v229, v229 offset:4096
	ds_read_b32 v230, v230 offset:4096
	ds_read_b32 v231, v231 offset:4096
	ds_read_b32 v232, v232 offset:4096
	v_lshl_add_u32 v244, v246, 2, v242
	s_waitcnt lgkmcnt(8)
	ds_write_b32 v244, v224 offset:4608
	s_waitcnt lgkmcnt(7)
	ds_write_b32 v244, v225 offset:4864
	s_waitcnt lgkmcnt(6)
	ds_write_b32 v244, v226 offset:5120
	s_waitcnt lgkmcnt(5)
	ds_write_b32 v244, v227 offset:5376
	s_waitcnt lgkmcnt(4)
	ds_write_b32 v244, v228 offset:5632
	s_waitcnt lgkmcnt(3)
	ds_write_b32 v244, v229 offset:5888
	s_waitcnt lgkmcnt(2)
	ds_write_b32 v244, v230 offset:6144
	s_waitcnt lgkmcnt(1)
	ds_write_b32 v244, v231 offset:6400
	s_waitcnt lgkmcnt(0)
	ds_write_b32 v244, v232 offset:6656
	ds_read_b32 v240, v219 offset:4220
	v_add_u32_e32 v242, 148, v242
	v_mov_b32_e32 v243, 0x7f800000
	s_waitcnt lgkmcnt(0)
; #define MFMA32(a, b, c) __builtin_amdgcn_mfma_f32_32x32x16_bf16((a), (b), (c), 0, 0, 0)
; #define NEGINF (-__builtin_inff())
; DI int crow(int i, int h) { return (i & 3) + 8 * (i >> 2) + 4 * h; }
; template <class KP, class VP, class ACT, class FILL>
; DI void attn_loop(AttnSt& st, const bf16x8 (&qf)[4], int k0, int k1, size_t vstride, KP kp, VP vp, ACT act, FILL fill) {
;     ...
;   for (int kt = k0; kt <= k1; ++kt) {
;     const int kn = (kt < k1) ? kt + 1 : k1;
;     const int kn2 = (kt + 2 <= k1) ? kt + 2 : k1;
;     {
;       const bf16_t* v0 = vp(kn);
; #pragma unroll
;       for (int j = 0; j < 8; ++j) nxt.v[j] = *(const s16x4*)(v0 + 256 * j);
;     }
;     bf16x8 k2[4];
;     {
;       const bf16_t* krow = kp(kn2);
; #pragma unroll
;       for (int ss = 0; ss < 4; ++ss) k2[ss] = *(const bf16x8*)(krow + 512 * ss);
;     }
;     f32x16 s_next;
; #pragma unroll
;     for (int i = 0; i < 16; ++i) s_next[i] = 0.f;
; #pragma unroll
;     for (int ss = 0; ss < 4; ++ss) s_next = MFMA32(nxt.k[ss], qf[ss], s_next);
; DI void nsa_main_item(const Params& p, int b, int head, int qb, const unsigned char* blut, const float* tbl) {
;     ...
;           int dist[16]; float bv[16];
; #pragma unroll
;           for (int i = 0; i < 16; ++i) dist[i] = t - (kt * 32 + crow(i, h));
;           bias16(blut, tblh, dist, bv);
; #pragma unroll
;           for (int i = 0; i < 16; ++i) lg[i] = (bs && dist[i] >= 0) ? s[i] + bv[i] : NEGINF;
.Lasel_loop:
	s_waitcnt vmcnt(16)
	v_mfma_f32_32x32x16_bf16 v[32:47], v[96:99], v[80:83], 0
	v_mfma_f32_32x32x16_bf16 v[48:63], v[112:115], v[80:83], 0
	v_mfma_f32_32x32x16_bf16 v[32:47], v[100:103], v[84:87], v[32:47]
	v_mfma_f32_32x32x16_bf16 v[48:63], v[116:119], v[84:87], v[48:63]
	v_mfma_f32_32x32x16_bf16 v[32:47], v[104:107], v[88:91], v[32:47]
	v_mfma_f32_32x32x16_bf16 v[48:63], v[120:123], v[88:91], v[48:63]
	v_mfma_f32_32x32x16_bf16 v[32:47], v[108:111], v[92:95], v[32:47]
	v_mfma_f32_32x32x16_bf16 v[48:63], v[124:127], v[92:95], v[48:63]
	s_add_u32 s23, s56, 2
	s_min_u32 s24, s23, s60
	s_lshl_b32 s26, s24, 12
	s_mov_b32 s27, 0
	v_lshl_add_u64 v[248:249], v[148:149], 0, s[26:27]
	global_load_dwordx4 v[96:99], v[248:249], off
	global_load_dwordx4 v[100:103], v[248:249], off offset:1024
	global_load_dwordx4 v[104:107], v[248:249], off offset:2048
	global_load_dwordx4 v[108:111], v[248:249], off offset:3072
	s_add_u32 s23, s56, 3
	s_min_u32 s24, s23, s60
	s_lshl_b32 s26, s24, 12
	s_mov_b32 s27, 0
	v_lshl_add_u64 v[248:249], v[148:149], 0, s[26:27]
	global_load_dwordx4 v[112:115], v[248:249], off
	global_load_dwordx4 v[116:119], v[248:249], off offset:1024
	global_load_dwordx4 v[120:123], v[248:249], off offset:2048
	global_load_dwordx4 v[124:127], v[248:249], off offset:3072
	s_sub_i32 s61, s60, s56
	s_lshr_b32 s23, s56, 1
	v_lshrrev_b64 v[248:249], s23, v[168:169]
	v_and_b32_e32 v248, 1, v248
	v_cmp_eq_u32_e64 s[62:63], 1, v248
	s_cmp_ge_i32 s61, 50
	s_cbranch_scc1 .Lasel_far
	s_lshl_b32 s23, s61, 5
	v_add_u32_e32 v241, s23, v221
	v_lshl_add_u32 v244, v241, 2, v242
	v_subrev_u32_e32 v245, 128, v244
	ds_read_b32 v224, v244 offset:108
	ds_read_b32 v225, v244 offset:104
	ds_read_b32 v226, v244 offset:100
	ds_read_b32 v227, v244 offset:96
	ds_read_b32 v228, v244 offset:76
	ds_read_b32 v229, v244 offset:72
	ds_read_b32 v230, v244 offset:68
	ds_read_b32 v231, v244 offset:64
	ds_read_b32 v232, v244 offset:44
	ds_read_b32 v233, v244 offset:40
	ds_read_b32 v234, v244 offset:36
	ds_read_b32 v235, v244 offset:32
	ds_read_b32 v236, v244 offset:12
	ds_read_b32 v237, v244 offset:8
	ds_read_b32 v238, v244 offset:4
	ds_read_b32 v239, v244 offset:0
	s_waitcnt lgkmcnt(8)
	v_add_f32_e32 v32, v32, v224
	v_add_f32_e32 v33, v33, v225
	v_add_f32_e32 v34, v34, v226
	v_add_f32_e32 v35, v35, v227
	v_add_f32_e32 v36, v36, v228
	v_add_f32_e32 v37, v37, v229
	v_add_f32_e32 v38, v38, v230
	v_add_f32_e32 v39, v39, v231
	s_waitcnt lgkmcnt(0)
	v_add_f32_e32 v40, v40, v232
	v_add_f32_e32 v41, v41, v233
	v_add_f32_e32 v42, v42, v234
	v_add_f32_e32 v43, v43, v235
	v_add_f32_e32 v44, v44, v236
	v_add_f32_e32 v45, v45, v237
	v_add_f32_e32 v46, v46, v238
	v_add_f32_e32 v47, v47, v239
	ds_read_b32 v224, v245 offset:108
	ds_read_b32 v225, v245 offset:104
	ds_read_b32 v226, v245 offset:100
	ds_read_b32 v227, v245 offset:96
	ds_read_b32 v228, v245 offset:76
	ds_read_b32 v229, v245 offset:72
	ds_read_b32 v230, v245 offset:68
	ds_read_b32 v231, v245 offset:64
	ds_read_b32 v232, v245 offset:44
	ds_read_b32 v233, v245 offset:40
	ds_read_b32 v234, v245 offset:36
	ds_read_b32 v235, v245 offset:32
	ds_read_b32 v236, v245 offset:12
	ds_read_b32 v237, v245 offset:8
	ds_read_b32 v238, v245 offset:4
	ds_read_b32 v239, v245 offset:0
	s_waitcnt lgkmcnt(8)
	v_add_f32_e32 v48, v48, v224
	v_add_f32_e32 v49, v49, v225
	v_add_f32_e32 v50, v50, v226
	v_add_f32_e32 v51, v51, v227
	v_add_f32_e32 v52, v52, v228
	v_add_f32_e32 v53, v53, v229
	v_add_f32_e32 v54, v54, v230
	v_add_f32_e32 v55, v55, v231
	s_waitcnt lgkmcnt(0)
	v_add_f32_e32 v56, v56, v232
	v_add_f32_e32 v57, v57, v233
	v_add_f32_e32 v58, v58, v234
	v_add_f32_e32 v59, v59, v235
	v_add_f32_e32 v60, v60, v236
	v_add_f32_e32 v61, v61, v237
	v_add_f32_e32 v62, v62, v238
	v_add_f32_e32 v63, v63, v239
	s_cmp_ge_i32 s61, 2
	s_cbranch_scc1 .Lasel_softmax
	v_subrev_u32_e32 v246, 32, v241
	v_cmp_le_i32_e32 vcc, 0, v241
	s_nop 1
	v_cndmask_b32_e32 v32, v199, v32, vcc
	v_cmp_le_i32_e32 vcc, 1, v241
	s_nop 1
	v_cndmask_b32_e32 v33, v199, v33, vcc
	v_cmp_le_i32_e32 vcc, 2, v241
	s_nop 1
	v_cndmask_b32_e32 v34, v199, v34, vcc
	v_cmp_le_i32_e32 vcc, 3, v241
	s_nop 1
	v_cndmask_b32_e32 v35, v199, v35, vcc
	v_cmp_le_i32_e32 vcc, 8, v241
	s_nop 1
	v_cndmask_b32_e32 v36, v199, v36, vcc
	v_cmp_le_i32_e32 vcc, 9, v241
	s_nop 1
	v_cndmask_b32_e32 v37, v199, v37, vcc
	v_cmp_le_i32_e32 vcc, 10, v241
	s_nop 1
	v_cndmask_b32_e32 v38, v199, v38, vcc
	v_cmp_le_i32_e32 vcc, 11, v241
	s_nop 1
	v_cndmask_b32_e32 v39, v199, v39, vcc
	v_cmp_le_i32_e32 vcc, 16, v241
	s_nop 1
	v_cndmask_b32_e32 v40, v199, v40, vcc
	v_cmp_le_i32_e32 vcc, 17, v241
	s_nop 1
	v_cndmask_b32_e32 v41, v199, v41, vcc
	v_cmp_le_i32_e32 vcc, 18, v241
	s_nop 1
	v_cndmask_b32_e32 v42, v199, v42, vcc
	v_cmp_le_i32_e32 vcc, 19, v241
	s_nop 1
	v_cndmask_b32_e32 v43, v199, v43, vcc
	v_cmp_le_i32_e32 vcc, 24, v241
	s_nop 1
	v_cndmask_b32_e32 v44, v199, v44, vcc
	v_cmp_le_i32_e32 vcc, 25, v241
	s_nop 1
	v_cndmask_b32_e32 v45, v199, v45, vcc
	v_cmp_le_i32_e32 vcc, 26, v241
	s_nop 1
	v_cndmask_b32_e32 v46, v199, v46, vcc
	v_cmp_le_i32_e32 vcc, 27, v241
	s_nop 1
	v_cndmask_b32_e32 v47, v199, v47, vcc
	v_cmp_le_i32_e32 vcc, 0, v246
	s_nop 1
	v_cndmask_b32_e32 v48, v199, v48, vcc
	v_cmp_le_i32_e32 vcc, 1, v246
	s_nop 1
	v_cndmask_b32_e32 v49, v199, v49, vcc
	v_cmp_le_i32_e32 vcc, 2, v246
	s_nop 1
	v_cndmask_b32_e32 v50, v199, v50, vcc
	v_cmp_le_i32_e32 vcc, 3, v246
	s_nop 1
	v_cndmask_b32_e32 v51, v199, v51, vcc
	v_cmp_le_i32_e32 vcc, 8, v246
	s_nop 1
	v_cndmask_b32_e32 v52, v199, v52, vcc
	v_cmp_le_i32_e32 vcc, 9, v246
	s_nop 1
	v_cndmask_b32_e32 v53, v199, v53, vcc
	v_cmp_le_i32_e32 vcc, 10, v246
	s_nop 1
	v_cndmask_b32_e32 v54, v199, v54, vcc
	v_cmp_le_i32_e32 vcc, 11, v246
	s_nop 1
	v_cndmask_b32_e32 v55, v199, v55, vcc
	v_cmp_le_i32_e32 vcc, 16, v246
	s_nop 1
	v_cndmask_b32_e32 v56, v199, v56, vcc
	v_cmp_le_i32_e32 vcc, 17, v246
	s_nop 1
	v_cndmask_b32_e32 v57, v199, v57, vcc
	v_cmp_le_i32_e32 vcc, 18, v246
	s_nop 1
	v_cndmask_b32_e32 v58, v199, v58, vcc
	v_cmp_le_i32_e32 vcc, 19, v246
	s_nop 1
	v_cndmask_b32_e32 v59, v199, v59, vcc
	v_cmp_le_i32_e32 vcc, 24, v246
	s_nop 1
	v_cndmask_b32_e32 v60, v199, v60, vcc
	v_cmp_le_i32_e32 vcc, 25, v246
	s_nop 1
	v_cndmask_b32_e32 v61, v199, v61, vcc
	v_cmp_le_i32_e32 vcc, 26, v246
	s_nop 1
	v_cndmask_b32_e32 v62, v199, v62, vcc
	v_cmp_le_i32_e32 vcc, 27, v246
	s_nop 1
	v_cndmask_b32_e32 v63, v199, v63, vcc
	s_branch .Lasel_softmax

; #define NEGINF (-__builtin_inff())
; DI float shx32(float v) { const auto r = __builtin_amdgcn_permlane32_swap(__float_as_uint(v), __float_as_uint(v), false, false); return __uint_as_float((threadIdx.x & 32) ? r[0] : r[1]); }
; DI float ex2(float x) { return __builtin_amdgcn_exp2f(x); }
; DI void softmax_step_r(AttnSt& st, const float (&lg)[16], const KVT& t) {
;   float mx = NEGINF;
; #pragma unroll
;   for (int i = 0; i < 16; ++i) mx = fmaxf(mx, lg[i]);
;   mx = fmaxf(mx, shx32(mx));
;   if (__ballot(mx > NEGINF) == 0ull) return;
;   const float mnew = fmaxf(st.m, mx);
;   const float muse = (mnew == NEGINF) ? 0.f : mnew;
;   const float alpha = ex2(st.m - muse);
;   float pr[16]; float rs = 0.f;
; #pragma unroll
;   for (int i = 0; i < 16; ++i) { pr[i] = ex2(lg[i] - muse); rs += pr[i]; }
;   st.l = st.l * alpha + rs;
;   if (__ballot(mnew != st.m) != 0ull) {
; #pragma unroll
;     for (int i = 0; i < 16; ++i) { st.o0[i] *= alpha; st.o1[i] *= alpha; }
;   }
;   st.m = mnew;
.Lasel_softmax:
	v_max3_f32 v224, v32, v33, v34
	v_max3_f32 v225, v40, v41, v42
	v_max3_f32 v226, v48, v49, v50
	v_max3_f32 v227, v56, v57, v58
	v_max3_f32 v224, v224, v35, v36
	v_max3_f32 v225, v225, v43, v44
	v_max3_f32 v226, v226, v51, v52
	v_max3_f32 v227, v227, v59, v60
	v_max3_f32 v224, v224, v37, v38
	v_max3_f32 v225, v225, v45, v46
	v_max3_f32 v226, v226, v53, v54
	v_max3_f32 v227, v227, v61, v62
	v_max_f32_e32 v224, v224, v39
	v_max_f32_e32 v225, v225, v47
	v_max_f32_e32 v226, v226, v55
	v_max_f32_e32 v227, v227, v63
	v_max3_f32 v224, v224, v225, v226
	v_max_f32_e32 v224, v224, v227
	v_mov_b32_e32 v225, v224
	v_mov_b32_e32 v226, v224
	s_nop 1
	v_permlane32_swap_b32_e32 v225, v226
	v_cndmask_b32_e64 v225, v225, v226, s[12:13]
	v_max_f32_e32 v224, v224, v225
	v_cndmask_b32_e64 v224, v199, v224, s[62:63]
	v_max_f32_e32 v225, v223, v224
	v_cmp_neq_f32_e32 vcc, v199, v225
	s_nop 1
	v_cndmask_b32_e32 v226, 0, v225, vcc
	v_sub_f32_e32 v227, v223, v226
	v_exp_f32_e32 v227, v227
	v_cndmask_b32_e64 v226, v243, v226, s[62:63]
	v_cmp_neq_f32_e32 vcc, v223, v225
	v_mov_b32_e32 v223, v225
	v_sub_f32_e32 v32, v32, v226
	v_sub_f32_e32 v33, v33, v226
	v_sub_f32_e32 v34, v34, v226
	v_sub_f32_e32 v35, v35, v226
	v_sub_f32_e32 v36, v36, v226
	v_sub_f32_e32 v37, v37, v226
	v_sub_f32_e32 v38, v38, v226
	v_sub_f32_e32 v39, v39, v226
	v_sub_f32_e32 v40, v40, v226
	v_sub_f32_e32 v41, v41, v226
	v_sub_f32_e32 v42, v42, v226
	v_sub_f32_e32 v43, v43, v226
	v_sub_f32_e32 v44, v44, v226
	v_sub_f32_e32 v45, v45, v226
	v_sub_f32_e32 v46, v46, v226
	v_sub_f32_e32 v47, v47, v226
	v_sub_f32_e32 v48, v48, v226
	v_sub_f32_e32 v49, v49, v226
	v_sub_f32_e32 v50, v50, v226
	v_sub_f32_e32 v51, v51, v226
	v_sub_f32_e32 v52, v52, v226
	v_sub_f32_e32 v53, v53, v226
	v_sub_f32_e32 v54, v54, v226
	v_sub_f32_e32 v55, v55, v226
	v_sub_f32_e32 v56, v56, v226
	v_sub_f32_e32 v57, v57, v226
	v_sub_f32_e32 v58, v58, v226
	v_sub_f32_e32 v59, v59, v226
	v_sub_f32_e32 v60, v60, v226
	v_sub_f32_e32 v61, v61, v226
	v_sub_f32_e32 v62, v62, v226
	v_sub_f32_e32 v63, v63, v226
	v_exp_f32_e32 v32, v32
	v_exp_f32_e32 v33, v33
	v_exp_f32_e32 v34, v34
	v_exp_f32_e32 v35, v35
	v_exp_f32_e32 v36, v36
	v_exp_f32_e32 v37, v37
	v_exp_f32_e32 v38, v38
	v_exp_f32_e32 v39, v39
	v_exp_f32_e32 v40, v40
	v_exp_f32_e32 v41, v41
	v_exp_f32_e32 v42, v42
	v_exp_f32_e32 v43, v43
	v_exp_f32_e32 v44, v44
	v_exp_f32_e32 v45, v45
	v_exp_f32_e32 v46, v46
	v_exp_f32_e32 v47, v47
	v_exp_f32_e32 v48, v48
	v_exp_f32_e32 v49, v49
	v_exp_f32_e32 v50, v50
	v_exp_f32_e32 v51, v51
	v_exp_f32_e32 v52, v52
	v_exp_f32_e32 v53, v53
	v_exp_f32_e32 v54, v54
	v_exp_f32_e32 v55, v55
	v_exp_f32_e32 v56, v56
	v_exp_f32_e32 v57, v57
	v_exp_f32_e32 v58, v58
	v_exp_f32_e32 v59, v59
	v_exp_f32_e32 v60, v60
	v_exp_f32_e32 v61, v61
	v_exp_f32_e32 v62, v62
	v_exp_f32_e32 v63, v63
	v_add_f32_e32 v228, v32, v33
	v_add_f32_e32 v229, v40, v41
	v_add_f32_e32 v230, v48, v49
	v_add_f32_e32 v231, v56, v57
	v_add_f32_e32 v228, v228, v34
	v_add_f32_e32 v229, v229, v42
	v_add_f32_e32 v230, v230, v50
	v_add_f32_e32 v231, v231, v58
	v_add_f32_e32 v228, v228, v35
	v_add_f32_e32 v229, v229, v43
	v_add_f32_e32 v230, v230, v51
	v_add_f32_e32 v231, v231, v59
	v_add_f32_e32 v228, v228, v36
	v_add_f32_e32 v229, v229, v44
	v_add_f32_e32 v230, v230, v52
	v_add_f32_e32 v231, v231, v60
	v_add_f32_e32 v228, v228, v37
	v_add_f32_e32 v229, v229, v45
	v_add_f32_e32 v230, v230, v53
	v_add_f32_e32 v231, v231, v61
	v_add_f32_e32 v228, v228, v38
	v_add_f32_e32 v229, v229, v46
	v_add_f32_e32 v230, v230, v54
	v_add_f32_e32 v231, v231, v62
	v_add_f32_e32 v228, v228, v39
	v_add_f32_e32 v229, v229, v47
	v_add_f32_e32 v230, v230, v55
	v_add_f32_e32 v231, v231, v63
	v_add_f32_e32 v228, v228, v229
	v_add_f32_e32 v230, v230, v231
	v_add_f32_e32 v228, v228, v230
	v_fma_f32 v222, v222, v227, v228
	s_cbranch_vccz .Lasel_noscale
	v_mul_f32_e32 v0, v227, v0
	v_mul_f32_e32 v1, v227, v1
	v_mul_f32_e32 v2, v227, v2
	v_mul_f32_e32 v3, v227, v3
	v_mul_f32_e32 v4, v227, v4
	v_mul_f32_e32 v5, v227, v5
	v_mul_f32_e32 v6, v227, v6
	v_mul_f32_e32 v7, v227, v7
	v_mul_f32_e32 v8, v227, v8
	v_mul_f32_e32 v9, v227, v9
	v_mul_f32_e32 v10, v227, v10
	v_mul_f32_e32 v11, v227, v11
	v_mul_f32_e32 v12, v227, v12
	v_mul_f32_e32 v13, v227, v13
	v_mul_f32_e32 v14, v227, v14
	v_mul_f32_e32 v15, v227, v15
	v_mul_f32_e32 v16, v227, v16
	v_mul_f32_e32 v17, v227, v17
	v_mul_f32_e32 v18, v227, v18
	v_mul_f32_e32 v19, v227, v19
	v_mul_f32_e32 v20, v227, v20
	v_mul_f32_e32 v21, v227, v21
	v_mul_f32_e32 v22, v227, v22
	v_mul_f32_e32 v23, v227, v23
	v_mul_f32_e32 v24, v227, v24
	v_mul_f32_e32 v25, v227, v25
	v_mul_f32_e32 v26, v227, v26
	v_mul_f32_e32 v27, v227, v27
	v_mul_f32_e32 v28, v227, v28
	v_mul_f32_e32 v29, v227, v29
	v_mul_f32_e32 v30, v227, v30
	v_mul_f32_e32 v31, v227, v31
; #define MFMA32(a, b, c) __builtin_amdgcn_mfma_f32_32x32x16_bf16((a), (b), (c), 0, 0, 0)
; DI unsigned pack2(float a, float b) { unsigned r; asm("v_cvt_pk_bf16_f32 %0, %1, %2" : "=v"(r) : "v"(a), "v"(b)); return r; }
; DI void softmax_step_r(AttnSt& st, const float (&lg)[16], const KVT& t) {
;     ...
; #pragma unroll
;   for (int s2 = 0; s2 < 2; ++s2) {
;     u32x4 pk; pk.x = pack2(pr[8 * s2], pr[8 * s2 + 1]); pk.y = pack2(pr[8 * s2 + 2], pr[8 * s2 + 3]); pk.z = pack2(pr[8 * s2 + 4], pr[8 * s2 + 5]); pk.w = pack2(pr[8 * s2 + 6], pr[8 * s2 + 7]);
;     const bf16x8 pb = __builtin_bit_cast(bf16x8, pk);
;     const bf16x8 va0 = __builtin_shufflevector(t.v[s2 * 4 + 0], t.v[s2 * 4 + 1], 0, 1, 2, 3, 4, 5, 6, 7);
;     st.o0 = MFMA32(va0, pb, st.o0);
;     const bf16x8 va1 = __builtin_shufflevector(t.v[s2 * 4 + 2], t.v[s2 * 4 + 3], 0, 1, 2, 3, 4, 5, 6, 7);
;     st.o1 = MFMA32(va1, pb, st.o1);
;   }
; template <class KP, class VP, class ACT, class FILL>
; DI void attn_loop(AttnSt& st, const bf16x8 (&qf)[4], int k0, int k1, size_t vstride, KP kp, VP vp, ACT act, FILL fill) {
;     ...
;     {
;       const bf16_t* v0 = vp(kn);
; #pragma unroll
;       for (int j = 0; j < 8; ++j) nxt.v[j] = *(const s16x4*)(v0 + 256 * j);
;     }
.Lasel_noscale:
	v_cvt_pk_bf16_f32 v224, v32, v33
	v_cvt_pk_bf16_f32 v225, v34, v35
	v_cvt_pk_bf16_f32 v226, v36, v37
	v_cvt_pk_bf16_f32 v227, v38, v39
	v_cvt_pk_bf16_f32 v228, v40, v41
	v_cvt_pk_bf16_f32 v229, v42, v43
	v_cvt_pk_bf16_f32 v230, v44, v45
	v_cvt_pk_bf16_f32 v231, v46, v47
	v_cvt_pk_bf16_f32 v232, v48, v49
	v_cvt_pk_bf16_f32 v233, v50, v51
	v_cvt_pk_bf16_f32 v234, v52, v53
	v_cvt_pk_bf16_f32 v235, v54, v55
	v_cvt_pk_bf16_f32 v236, v56, v57
	v_cvt_pk_bf16_f32 v237, v58, v59
	v_cvt_pk_bf16_f32 v238, v60, v61
	v_cvt_pk_bf16_f32 v239, v62, v63
	s_waitcnt vmcnt(8)
	s_nop 1
	v_mfma_f32_32x32x16_bf16 v[0:15], v[64:67], v[224:227], v[0:15]
	v_mfma_f32_32x32x16_bf16 v[16:31], v[68:71], v[224:227], v[16:31]
	v_mfma_f32_32x32x16_bf16 v[0:15], v[72:75], v[228:231], v[0:15]
	v_mfma_f32_32x32x16_bf16 v[16:31], v[76:79], v[228:231], v[16:31]
	v_mfma_f32_32x32x16_bf16 v[0:15], v[172:175], v[232:235], v[0:15]
	v_mfma_f32_32x32x16_bf16 v[16:31], v[176:179], v[232:235], v[16:31]
	v_mfma_f32_32x32x16_bf16 v[0:15], v[180:183], v[236:239], v[0:15]
	v_mfma_f32_32x32x16_bf16 v[16:31], v[184:187], v[236:239], v[16:31]
	s_add_u32 s23, s56, 2
	s_min_u32 s24, s23, s60
	s_lshl_b32 s26, s24, 12
	s_mov_b32 s27, 0
	v_lshl_add_u64 v[250:251], v[170:171], 0, s[26:27]
	global_load_dwordx2 v[64:65], v[250:251], off
	global_load_dwordx2 v[66:67], v[250:251], off offset:512
	global_load_dwordx2 v[68:69], v[250:251], off offset:1024
	global_load_dwordx2 v[70:71], v[250:251], off offset:1536
	global_load_dwordx2 v[72:73], v[250:251], off offset:2048
	global_load_dwordx2 v[74:75], v[250:251], off offset:2560
	global_load_dwordx2 v[76:77], v[250:251], off offset:3072
	global_load_dwordx2 v[78:79], v[250:251], off offset:3584
	s_add_u32 s23, s56, 3
	s_min_u32 s24, s23, s60
	s_lshl_b32 s26, s24, 12
	s_mov_b32 s27, 0
	v_lshl_add_u64 v[250:251], v[170:171], 0, s[26:27]
	global_load_dwordx2 v[172:173], v[250:251], off
	global_load_dwordx2 v[174:175], v[250:251], off offset:512
	global_load_dwordx2 v[176:177], v[250:251], off offset:1024
	global_load_dwordx2 v[178:179], v[250:251], off offset:1536
	global_load_dwordx2 v[180:181], v[250:251], off offset:2048
	global_load_dwordx2 v[182:183], v[250:251], off offset:2560
	global_load_dwordx2 v[184:185], v[250:251], off offset:3072
	global_load_dwordx2 v[186:187], v[250:251], off offset:3584
	s_add_u32 s56, s56, 2
	s_cmp_le_u32 s56, s60
	s_cbranch_scc1 .Lasel_loop
	s_nop 15
	s_waitcnt vmcnt(0)
	s_mov_b64 s[58:59], 0
	s_branch .LBB0_701

; DI void filler_items(const Params& p, int layer, char* lds, int which) {
;   __syncthreads();
;   unsigned char* blut = (unsigned char*)lds; float* tbl = (float*)(lds + 4096);
;   build_lut(blut, tbl, p.in[I_RELB]);
;   unsigned* ctr = (unsigned*)(p.ws + OFF_MISC) + 16 + layer * 2 + which;
;   for (;;) {
;     const int item = wave_fetch(ctr);
;     if (which == 0) {
;       if (item >= 128 * 16 + 96 * 48) break;
;       if (item < 128 * 16) { const int qb = 127 - item / 16, sub = item % 16; dil_item(p, sub >> 1, sub & 1, qb, blut, tbl); }
;       else { const int it2 = item - 128 * 16, qb = 127 - it2 / 48, sub = it2 % 48; nsa_win_item(p, sub / 6, sub % 6, qb, blut, tbl); }
;     }
;     else { if (item >= 128 * 32) break; const int qb = 127 - item / 32, sub = item % 32; moba_item(p, sub >> 2, sub & 3, qb, blut, tbl); }
.LBB0_932:
	s_or_b64 exec, exec, s[8:9]
	v_readlane_b32 s10, v254, 1
	s_and_b32 s10, s10, 7
	s_lshl_b32 s10, s10, 2
	s_mov_b32 s101, s10
	s_lshl_b32 s11, s47, 5
	s_add_u32 s10, s10, s11
	s_add_u32 s10, s10, 0x65c00c0
	s_add_u32 s10, s34, s10
	s_addc_u32 s11, s35, 0
	s_mov_b64 s[14:15], 0
	s_waitcnt lgkmcnt(0)
	s_barrier
	s_branch .LBB0_935

; #define MFMA32(a, b, c) __builtin_amdgcn_mfma_f32_32x32x16_bf16((a), (b), (c), 0, 0, 0)
; #define NEGINF (-__builtin_inff())
; #define TIDX get_tid_()
; DI float shx32(float v) { const auto r = __builtin_amdgcn_permlane32_swap(__float_as_uint(v), __float_as_uint(v), false, false); return __uint_as_float((threadIdx.x & 32) ? r[0] : r[1]); }
; DI void moba_item(const Params& p, int b, int hd, int qb, const unsigned char* blut, const float* tbl) {
;   const int lane = TIDX & 63, r = lane & 31, h = lane >> 5;
;   const int bh = b * 4 + hd;
;   const int t = qb * 32 + r;
;   const int c = qb >> 3;
;   const float* tblh = tbl + (6 + hd) * 32;
;   bf16x8 qf[4];
;   load_q(qf, (const bf16_t*)(p.ws + OFF_QM) + (size_t)(b * 4096 + t) * 256 + hd * 64 + 8 * h);
;   unsigned mmask = 0u;
;   if (c > 0) {
;     const bf16_t* km = (const bf16_t*)(p.ws + OFF_KMEAN) + (size_t)bh * 16 * 64 + (size_t)(r & 15) * 64 + 8 * h;
;     f32x16 s;
; #pragma unroll
;     for (int i = 0; i < 16; ++i) s[i] = 0.f;
; #pragma unroll
;     for (int ss = 0; ss < 4; ++ss) {
;       bf16x8 kf = *(const bf16x8*)(km + 16 * ss);
;       if (r >= 16) {
; #pragma unroll
;         for (int j = 0; j < 8; ++j) kf[j] = 0;
;       }
;       s = MFMA32(kf, qf[ss], s);
;     }
;     float g16[16];
; #pragma unroll
;     for (int i = 0; i < 8; ++i) {
;       const float own = s[i], oth = shx32(own);
;       const int base = (i & 3) + 8 * (i >> 2);
;       g16[base] = h ? oth : own;
;       g16[base + 4] = h ? own : oth;
;     }
; #pragma unroll
;     for (int n = 0; n < 16; ++n) g16[n] = (n < c) ? g16[n] : NEGINF;
; DI void filler_items(const Params& p, int layer, char* lds, int which) {
;     ...
;     else { if (item >= 128 * 32) break; const int qb = 127 - item / 32, sub = item % 32; moba_item(p, sub >> 2, sub & 3, qb, blut, tbl); }
.LBB0_939:
	s_or_b64 exec, exec, s[8:9]
	v_lshlrev_b32_e32 v1, 2, v188
	v_and_b32_e32 v1, 0x100, v1
	ds_bpermute_b32 v0, v1, v0
	s_movk_i32 s8, 0x200
	s_waitcnt lgkmcnt(0)
	v_cmp_gt_i32_e32 vcc, s8, v0
	s_mov_b64 s[8:9], -1
	s_and_saveexec_b64 s[54:55], vcc
	s_cbranch_execz .LBB0_934
	v_lshrrev_b32_e32 v1, 2, v0
	v_mul_u32_u24_e32 v1, 28, v1
	v_add3_u32 v0, v0, v1, s101
	v_ashrrev_i32_e32 v1, 31, v0
	v_lshrrev_b32_e32 v1, 27, v1
	v_add_u32_e32 v1, v0, v1
	v_ashrrev_i32_e32 v21, 5, v1
	v_and_b32_e32 v1, 0xffffffe0, v1
	v_sub_u32_e32 v16, v0, v1
	v_mov_b32_e32 v0, v129
	v_sub_u32_e32 v154, 0x7f, v21
	v_lshlrev_b32_e32 v1, 10, v16
	v_and_b32_e32 v18, 31, v0
	v_bfe_u32 v19, v0, 5, 1
	v_lshl_or_b32 v0, v154, 5, v18
	v_and_b32_e32 v1, 0xfffff000, v1
	v_add_u32_e32 v132, v0, v1
	v_ashrrev_i32_e32 v133, 31, v132
	v_readlane_b32 s8, v253, 45
	v_and_b32_e32 v20, 3, v16
	v_lshlrev_b64 v[0:1], 9, v[132:133]
	v_readlane_b32 s9, v253, 46
	v_lshlrev_b32_e32 v130, 7, v20
	v_cmp_lt_u32_e32 vcc, 7, v154
	v_lshl_add_u64 v[0:1], s[8:9], 0, v[0:1]
	v_lshl_add_u64 v[0:1], v[0:1], 0, v[130:131]
	v_lshlrev_b32_e32 v130, 4, v19
	v_lshl_add_u64 v[0:1], v[0:1], 0, v[130:131]
	global_load_dwordx4 v[80:83], v[0:1], off
	global_load_dwordx4 v[84:87], v[0:1], off offset:32
	global_load_dwordx4 v[88:91], v[0:1], off offset:64
	global_load_dwordx4 v[92:95], v[0:1], off offset:96
	v_ashrrev_i32_e32 v17, 31, v16
	s_and_saveexec_b64 s[8:9], vcc
	s_xor_b64 s[8:9], exec, s[8:9]
	s_cbranch_execz .LBB0_942
	v_readlane_b32 s24, v253, 47
	v_lshlrev_b64 v[0:1], 11, v[16:17]
	v_readlane_b32 s25, v253, 48
	v_lshlrev_b32_e32 v3, 7, v18
	v_lshlrev_b32_e32 v2, 3, v19
	v_lshl_add_u64 v[0:1], s[24:25], 0, v[0:1]
	v_and_b32_e32 v130, 0x780, v3
	v_lshl_add_u64 v[0:1], v[0:1], 0, v[130:131]
	v_lshlrev_b32_e32 v130, 1, v2
	v_lshl_add_u64 v[26:27], v[0:1], 0, v[130:131]
	global_load_dwordx4 v[0:3], v[26:27], off
	global_load_dwordx4 v[22:25], v[26:27], off offset:32
	v_cmp_lt_u32_e32 vcc, 15, v18
	s_movk_i32 s23, 0x47
	s_waitcnt vmcnt(1)
	v_cndmask_b32_e64 v3, v3, 0, vcc
	v_cndmask_b32_e64 v2, v2, 0, vcc
	v_cndmask_b32_e64 v1, v1, 0, vcc
	v_cndmask_b32_e64 v0, v0, 0, vcc
	s_waitcnt vmcnt(0)
	v_cndmask_b32_e64 v25, v25, 0, vcc
	v_cndmask_b32_e64 v24, v24, 0, vcc
	v_mfma_f32_32x32x16_bf16 v[0:15], v[0:3], v[80:83], 0
	v_cndmask_b32_e64 v23, v23, 0, vcc
	v_cndmask_b32_e64 v22, v22, 0, vcc
	s_nop 1
	v_mfma_f32_32x32x16_bf16 v[0:15], v[22:25], v[84:87], v[0:15]
	global_load_dwordx4 v[22:25], v[26:27], off offset:64
	s_waitcnt vmcnt(0)
	v_cndmask_b32_e64 v25, v25, 0, vcc
	v_cndmask_b32_e64 v24, v24, 0, vcc
	v_cndmask_b32_e64 v23, v23, 0, vcc
	v_cndmask_b32_e64 v22, v22, 0, vcc
	s_nop 1
	v_mfma_f32_32x32x16_bf16 v[0:15], v[22:25], v[88:91], v[0:15]
	global_load_dwordx4 v[22:25], v[26:27], off offset:96
	s_waitcnt vmcnt(0)
	v_cndmask_b32_e64 v25, v25, 0, vcc
	v_cndmask_b32_e64 v24, v24, 0, vcc
	v_cndmask_b32_e64 v23, v23, 0, vcc
	v_cndmask_b32_e64 v22, v22, 0, vcc
	v_cmp_eq_u32_e32 vcc, 0, v19
	s_nop 0
	v_mfma_f32_32x32x16_bf16 v[0:15], v[22:25], v[92:95], v[0:15]
	s_nop 11
	v_mov_b32_e32 v8, v0
	v_mov_b32_e32 v9, v0
	s_nop 1
	v_permlane32_swap_b32_e32 v8, v9
	v_cndmask_b32_e64 v9, v8, v9, s[12:13]
	v_mov_b32_e32 v8, v1
	v_mov_b32_e32 v11, v1
	s_nop 1
	v_permlane32_swap_b32_e32 v8, v11
	v_cndmask_b32_e64 v8, v8, v11, s[12:13]
	v_cndmask_b32_e32 v11, v8, v1, vcc
	v_cndmask_b32_e32 v12, v1, v8, vcc
	v_mov_b32_e32 v1, v2
	v_mov_b32_e32 v8, v2
	s_nop 1
	v_permlane32_swap_b32_e32 v1, v8
	v_cndmask_b32_e64 v1, v1, v8, s[12:13]
	v_cndmask_b32_e32 v13, v1, v2, vcc
	v_cndmask_b32_e32 v14, v2, v1, vcc
	v_mov_b32_e32 v1, v3
	v_mov_b32_e32 v2, v3
	s_nop 1
	v_permlane32_swap_b32_e32 v1, v2
	v_cndmask_b32_e64 v1, v1, v2, s[12:13]
	v_cndmask_b32_e32 v15, v1, v3, vcc
	v_cndmask_b32_e32 v22, v3, v1, vcc
	v_mov_b32_e32 v1, v4
	v_mov_b32_e32 v2, v4
	s_nop 1
	v_permlane32_swap_b32_e32 v1, v2
	v_cndmask_b32_e64 v1, v1, v2, s[12:13]
	v_cndmask_b32_e32 v23, v1, v4, vcc
	v_cndmask_b32_e32 v24, v4, v1, vcc
	v_mov_b32_e32 v1, v5
	v_mov_b32_e32 v2, v5
	s_nop 1
	v_permlane32_swap_b32_e32 v1, v2
	v_cndmask_b32_e64 v1, v1, v2, s[12:13]
	v_cndmask_b32_e32 v25, v1, v5, vcc
	v_cndmask_b32_e32 v26, v5, v1, vcc
	v_mov_b32_e32 v1, v6
	v_mov_b32_e32 v2, v6
	s_nop 1
	v_permlane32_swap_b32_e32 v1, v2
	v_cndmask_b32_e64 v1, v1, v2, s[12:13]
	v_cndmask_b32_e32 v27, v1, v6, vcc
	v_cndmask_b32_e32 v28, v6, v1, vcc
	v_mov_b32_e32 v1, v7
	v_mov_b32_e32 v2, v7
	s_nop 1
	v_permlane32_swap_b32_e32 v1, v2
	v_cndmask_b32_e64 v1, v1, v2, s[12:13]
	v_cndmask_b32_e32 v10, v0, v9, vcc
	v_cndmask_b32_e32 v29, v1, v7, vcc
	v_cndmask_b32_e32 v8, v7, v1, vcc
	v_cndmask_b32_e32 v0, v9, v0, vcc
	v_cmp_lt_u32_e32 vcc, 15, v154
	s_nop 1
	v_cndmask_b32_e32 v1, v199, v11, vcc
	v_cmp_lt_u32_e32 vcc, 23, v154
	s_nop 1
	v_cndmask_b32_e32 v2, v199, v13, vcc
	v_cmp_lt_u32_e32 vcc, 31, v154
	s_nop 1
	v_cndmask_b32_e32 v3, v199, v15, vcc
	v_cmp_lt_u32_e32 vcc, 39, v154
	s_nop 1
	v_cndmask_b32_e32 v4, v199, v10, vcc
	v_cmp_lt_u32_e32 vcc, 47, v154
	s_nop 1
	v_cndmask_b32_e32 v5, v199, v12, vcc
	v_cmp_lt_u32_e32 vcc, 55, v154
	s_nop 1
	v_cndmask_b32_e32 v6, v199, v14, vcc
	v_cmp_lt_u32_e32 vcc, 63, v154
	s_nop 1
	v_cndmask_b32_e32 v7, v199, v22, vcc
	v_cmp_lt_u32_e32 vcc, s23, v154
	s_movk_i32 s23, 0x4f
	s_nop 0
	v_cndmask_b32_e32 v9, v199, v23, vcc
	v_cmp_lt_u32_e32 vcc, s23, v154
	s_movk_i32 s23, 0x57
	s_nop 0
	v_cndmask_b32_e32 v10, v199, v25, vcc
	v_cmp_lt_u32_e32 vcc, s23, v154
	s_movk_i32 s23, 0x5f
	s_nop 0
	v_cndmask_b32_e32 v11, v199, v27, vcc
	v_cmp_lt_u32_e32 vcc, s23, v154
	s_movk_i32 s23, 0x67
	s_nop 0
	v_cndmask_b32_e32 v12, v199, v29, vcc
; #define NEGINF (-__builtin_inff())
; DI void moba_item(const Params& p, int b, int hd, int qb, const unsigned char* blut, const float* tbl) {
;     ...
;     for (int round = 0; round < 3; ++round) {
;       float best = NEGINF; int bi = -1;
; #pragma unroll
;       for (int n = 0; n < 16; ++n) if (g16[n] > best) { best = g16[n]; bi = n; }
;       if (bi >= 0) mmask |= 1u << bi;
; #pragma unroll
;       for (int n = 0; n < 16; ++n) if (n == bi) g16[n] = NEGINF;
;     }
	v_cmp_lt_u32_e32 vcc, s23, v154
	s_movk_i32 s23, 0x6f
	s_nop 0
	v_cndmask_b32_e32 v13, v199, v24, vcc
	v_cmp_lt_u32_e32 vcc, s23, v154
	s_movk_i32 s23, 0x77
	s_nop 0
	v_cndmask_b32_e32 v14, v199, v26, vcc
	v_cmp_lt_u32_e32 vcc, s23, v154
	s_movk_i32 s23, 0x7f
	s_nop 0
	v_cndmask_b32_e32 v15, v199, v28, vcc
	v_cmp_lt_u32_e32 vcc, s23, v154
	s_nop 1
	v_cndmask_b32_e32 v8, v199, v8, vcc
	v_cmp_nlg_f32_e32 vcc, s5, v0
	s_nop 1
	v_cndmask_b32_e32 v22, v0, v199, vcc
	v_cndmask_b32_e64 v23, 0, -1, vcc
	v_cmp_gt_f32_e32 vcc, v1, v22
	s_nop 1
	v_cndmask_b32_e32 v22, v22, v1, vcc
	v_cndmask_b32_e64 v23, v23, 1, vcc
	v_cmp_gt_f32_e32 vcc, v2, v22
	s_nop 1
	v_cndmask_b32_e32 v22, v22, v2, vcc
	v_cndmask_b32_e64 v23, v23, 2, vcc
	v_cmp_gt_f32_e32 vcc, v3, v22
	s_nop 1
	v_cndmask_b32_e32 v22, v22, v3, vcc
	v_cndmask_b32_e64 v23, v23, 3, vcc
	v_cmp_gt_f32_e32 vcc, v4, v22
	s_nop 1
	v_cndmask_b32_e32 v22, v22, v4, vcc
	v_cndmask_b32_e64 v23, v23, 4, vcc
	v_cmp_gt_f32_e32 vcc, v5, v22
	s_nop 1
	v_cndmask_b32_e32 v22, v22, v5, vcc
	v_cndmask_b32_e64 v23, v23, 5, vcc
	v_cmp_gt_f32_e32 vcc, v6, v22
	s_nop 1
	v_cndmask_b32_e32 v22, v22, v6, vcc
	v_cndmask_b32_e64 v23, v23, 6, vcc
	v_cmp_gt_f32_e32 vcc, v7, v22
	s_nop 1
	v_cndmask_b32_e32 v22, v22, v7, vcc
	v_cndmask_b32_e64 v23, v23, 7, vcc
	v_cmp_gt_f32_e32 vcc, v9, v22
	s_nop 1
	v_cndmask_b32_e32 v22, v22, v9, vcc
	v_cndmask_b32_e64 v23, v23, 8, vcc
	v_cmp_gt_f32_e32 vcc, v10, v22
	s_nop 1
	v_cndmask_b32_e32 v22, v22, v10, vcc
	v_cndmask_b32_e64 v23, v23, 9, vcc
	v_cmp_gt_f32_e32 vcc, v11, v22
	s_nop 1
	v_cndmask_b32_e32 v22, v22, v11, vcc
	v_cndmask_b32_e64 v23, v23, 10, vcc
	v_cmp_gt_f32_e32 vcc, v12, v22
	s_nop 1
	v_cndmask_b32_e32 v22, v22, v12, vcc
	v_cndmask_b32_e64 v23, v23, 11, vcc
	v_cmp_gt_f32_e32 vcc, v13, v22
	s_nop 1
	v_cndmask_b32_e32 v22, v22, v13, vcc
	v_cndmask_b32_e64 v23, v23, 12, vcc
	v_cmp_gt_f32_e32 vcc, v14, v22
	s_nop 1
	v_cndmask_b32_e32 v22, v22, v14, vcc
	v_cndmask_b32_e64 v23, v23, 13, vcc
	v_cmp_gt_f32_e32 vcc, v15, v22
	s_nop 1
	v_cndmask_b32_e32 v22, v22, v15, vcc
	v_cndmask_b32_e64 v23, v23, 14, vcc
	v_cmp_ngt_f32_e32 vcc, v8, v22
	s_nop 1
	v_cndmask_b32_e32 v22, 15, v23, vcc
	v_lshlrev_b32_e64 v23, v22, 1
	v_cmp_lt_i32_e32 vcc, -1, v22
	s_nop 1
	v_cndmask_b32_e32 v23, 0, v23, vcc
	v_cmp_ne_u32_e32 vcc, 0, v22
	s_nop 1
	v_cndmask_b32_e32 v0, v199, v0, vcc
	v_cmp_ne_u32_e32 vcc, 1, v22
	s_nop 1
	v_cndmask_b32_e32 v1, v199, v1, vcc
	v_cmp_ne_u32_e32 vcc, 2, v22
	s_nop 1
	v_cndmask_b32_e32 v2, v199, v2, vcc
	v_cmp_ne_u32_e32 vcc, 3, v22
	s_nop 1
	v_cndmask_b32_e32 v3, v199, v3, vcc
	v_cmp_ne_u32_e32 vcc, 4, v22
	s_nop 1
	v_cndmask_b32_e32 v4, v199, v4, vcc
	v_cmp_ne_u32_e32 vcc, 5, v22
	s_nop 1
	v_cndmask_b32_e32 v5, v199, v5, vcc
	v_cmp_ne_u32_e32 vcc, 6, v22
	s_nop 1
	v_cndmask_b32_e32 v6, v199, v6, vcc
	v_cmp_ne_u32_e32 vcc, 7, v22
	s_nop 1
	v_cndmask_b32_e32 v7, v199, v7, vcc
	v_cmp_ne_u32_e32 vcc, 8, v22
	s_nop 1
	v_cndmask_b32_e32 v9, v199, v9, vcc
	v_cmp_ne_u32_e32 vcc, 9, v22
	s_nop 1
	v_cndmask_b32_e32 v10, v199, v10, vcc
	v_cmp_ne_u32_e32 vcc, 10, v22
	s_nop 1
	v_cndmask_b32_e32 v11, v199, v11, vcc
	v_cmp_ne_u32_e32 vcc, 11, v22
	s_nop 1
	v_cndmask_b32_e32 v12, v199, v12, vcc
	v_cmp_ne_u32_e32 vcc, 12, v22
	s_nop 1
	v_cndmask_b32_e32 v13, v199, v13, vcc
	v_cmp_ne_u32_e32 vcc, 13, v22
	s_nop 1
	v_cndmask_b32_e32 v14, v199, v14, vcc
	v_cmp_ne_u32_e32 vcc, 14, v22
	s_nop 1
	v_cndmask_b32_e32 v15, v199, v15, vcc
	v_cmp_ne_u32_e32 vcc, 15, v22
	s_nop 1
	v_cndmask_b32_e32 v8, v199, v8, vcc
	v_cmp_nlg_f32_e32 vcc, s5, v0
	s_nop 1
	v_cndmask_b32_e32 v22, v0, v199, vcc
	v_cndmask_b32_e64 v24, 0, -1, vcc
	v_cmp_gt_f32_e32 vcc, v1, v22
	s_nop 1
	v_cndmask_b32_e32 v22, v22, v1, vcc
	v_cndmask_b32_e64 v24, v24, 1, vcc
	v_cmp_gt_f32_e32 vcc, v2, v22
	s_nop 1
	v_cndmask_b32_e32 v22, v22, v2, vcc
	v_cndmask_b32_e64 v24, v24, 2, vcc
	v_cmp_gt_f32_e32 vcc, v3, v22
	s_nop 1
	v_cndmask_b32_e32 v22, v22, v3, vcc
	v_cndmask_b32_e64 v24, v24, 3, vcc
	v_cmp_gt_f32_e32 vcc, v4, v22
	s_nop 1
	v_cndmask_b32_e32 v22, v22, v4, vcc
	v_cndmask_b32_e64 v24, v24, 4, vcc
	v_cmp_gt_f32_e32 vcc, v5, v22
	s_nop 1
	v_cndmask_b32_e32 v22, v22, v5, vcc
	v_cndmask_b32_e64 v24, v24, 5, vcc
	v_cmp_gt_f32_e32 vcc, v6, v22
	s_nop 1
	v_cndmask_b32_e32 v22, v22, v6, vcc
	v_cndmask_b32_e64 v24, v24, 6, vcc
	v_cmp_gt_f32_e32 vcc, v7, v22
	s_nop 1
	v_cndmask_b32_e32 v22, v22, v7, vcc
	v_cndmask_b32_e64 v24, v24, 7, vcc
	v_cmp_gt_f32_e32 vcc, v9, v22
	s_nop 1
	v_cndmask_b32_e32 v22, v22, v9, vcc
	v_cndmask_b32_e64 v24, v24, 8, vcc
	v_cmp_gt_f32_e32 vcc, v10, v22
	s_nop 1
	v_cndmask_b32_e32 v22, v22, v10, vcc
	v_cndmask_b32_e64 v24, v24, 9, vcc
	v_cmp_gt_f32_e32 vcc, v11, v22
	s_nop 1
	v_cndmask_b32_e32 v22, v22, v11, vcc
	v_cndmask_b32_e64 v24, v24, 10, vcc
	v_cmp_gt_f32_e32 vcc, v12, v22
	s_nop 1
	v_cndmask_b32_e32 v22, v22, v12, vcc
	v_cndmask_b32_e64 v24, v24, 11, vcc
	v_cmp_gt_f32_e32 vcc, v13, v22
	s_nop 1
	v_cndmask_b32_e32 v22, v22, v13, vcc
	v_cndmask_b32_e64 v24, v24, 12, vcc
	v_cmp_gt_f32_e32 vcc, v14, v22
	s_nop 1
	v_cndmask_b32_e32 v22, v22, v14, vcc
	v_cndmask_b32_e64 v24, v24, 13, vcc
	v_cmp_gt_f32_e32 vcc, v15, v22
	s_nop 1
	v_cndmask_b32_e32 v22, v22, v15, vcc
	v_cndmask_b32_e64 v24, v24, 14, vcc
	v_cmp_ngt_f32_e32 vcc, v8, v22
	s_nop 1
	v_cndmask_b32_e32 v22, 15, v24, vcc
	v_lshlrev_b32_e64 v24, v22, 1
	v_cmp_lt_i32_e32 vcc, -1, v22
	s_nop 1
	v_cndmask_b32_e32 v24, 0, v24, vcc
	v_cmp_ne_u32_e32 vcc, 0, v22
	s_nop 1
	v_cndmask_b32_e32 v0, v199, v0, vcc
	v_cmp_ne_u32_e32 vcc, 1, v22
	s_nop 1
	v_cndmask_b32_e32 v1, v199, v1, vcc
	v_cmp_ne_u32_e32 vcc, 2, v22
	s_nop 1
	v_cndmask_b32_e32 v2, v199, v2, vcc
; #define NEGINF (-__builtin_inff())
; DI void moba_item(const Params& p, int b, int hd, int qb, const unsigned char* blut, const float* tbl) {
;     ...
;     for (int round = 0; round < 3; ++round) {
;       float best = NEGINF; int bi = -1;
; #pragma unroll
;       for (int n = 0; n < 16; ++n) if (g16[n] > best) { best = g16[n]; bi = n; }
;       if (bi >= 0) mmask |= 1u << bi;
; #pragma unroll
;       for (int n = 0; n < 16; ++n) if (n == bi) g16[n] = NEGINF;
;     }
;   }
;   mmask |= 1u << c;
;   const bf16_t* K = (const bf16_t*)(p.ws + OFF_KM) + (size_t)bh * 4096 * 64;
;   const bf16_t* Vt = (const bf16_t*)(p.ws + OFF_VMT) + (size_t)bh * 64 * 4096;
;   AttnSt st; attn_init(st);
;   attn_loop(st, qf, 0, qb, 32,
;     [&](int kt) { return K + (size_t)kt * 2048 + (h * 32 + r) * 8; },
;     [&](int kt) { return Vt + (size_t)kt * 2048 + (h * 32 + r) * 4; },
;     [&](int kt) { return __ballot((mmask >> (kt >> 3)) & 1u) != 0ull; },
;     [&](int kt, const f32x16& s, float (&lg)[16]) {
	v_cmp_ne_u32_e32 vcc, 3, v22
	s_nop 1
	v_cndmask_b32_e32 v3, v199, v3, vcc
	v_cmp_ne_u32_e32 vcc, 4, v22
	s_nop 1
	v_cndmask_b32_e32 v4, v199, v4, vcc
	v_cmp_ne_u32_e32 vcc, 5, v22
	s_nop 1
	v_cndmask_b32_e32 v5, v199, v5, vcc
	v_cmp_ne_u32_e32 vcc, 6, v22
	s_nop 1
	v_cndmask_b32_e32 v6, v199, v6, vcc
	v_cmp_ne_u32_e32 vcc, 7, v22
	s_nop 1
	v_cndmask_b32_e32 v7, v199, v7, vcc
	v_cmp_ne_u32_e32 vcc, 8, v22
	s_nop 1
	v_cndmask_b32_e32 v9, v199, v9, vcc
	v_cmp_ne_u32_e32 vcc, 9, v22
	s_nop 1
	v_cndmask_b32_e32 v10, v199, v10, vcc
	v_cmp_ne_u32_e32 vcc, 10, v22
	s_nop 1
	v_cndmask_b32_e32 v11, v199, v11, vcc
	v_cmp_ne_u32_e32 vcc, 11, v22
	s_nop 1
	v_cndmask_b32_e32 v12, v199, v12, vcc
	v_cmp_ne_u32_e32 vcc, 12, v22
	s_nop 1
	v_cndmask_b32_e32 v13, v199, v13, vcc
	v_cmp_ne_u32_e32 vcc, 13, v22
	s_nop 1
	v_cndmask_b32_e32 v14, v199, v14, vcc
	v_cmp_ne_u32_e32 vcc, 14, v22
	s_nop 1
	v_cndmask_b32_e32 v15, v199, v15, vcc
	v_cmp_ne_u32_e32 vcc, 15, v22
	s_nop 1
	v_cndmask_b32_e32 v8, v199, v8, vcc
	v_cmp_nlg_f32_e32 vcc, s5, v0
	s_nop 1
	v_cndmask_b32_e32 v0, v0, v199, vcc
	v_cndmask_b32_e64 v22, 0, -1, vcc
	v_cmp_gt_f32_e32 vcc, v1, v0
	s_nop 1
	v_cndmask_b32_e32 v0, v0, v1, vcc
	v_cndmask_b32_e64 v1, v22, 1, vcc
	v_cmp_gt_f32_e32 vcc, v2, v0
	s_nop 1
	v_cndmask_b32_e32 v0, v0, v2, vcc
	v_cndmask_b32_e64 v1, v1, 2, vcc
	v_cmp_gt_f32_e32 vcc, v3, v0
	s_nop 1
	v_cndmask_b32_e32 v0, v0, v3, vcc
	v_cndmask_b32_e64 v1, v1, 3, vcc
	v_cmp_gt_f32_e32 vcc, v4, v0
	s_nop 1
	v_cndmask_b32_e32 v0, v0, v4, vcc
	v_cndmask_b32_e64 v1, v1, 4, vcc
	v_cmp_gt_f32_e32 vcc, v5, v0
	s_nop 1
	v_cndmask_b32_e32 v0, v0, v5, vcc
	v_cndmask_b32_e64 v1, v1, 5, vcc
	v_cmp_gt_f32_e32 vcc, v6, v0
	s_nop 1
	v_cndmask_b32_e32 v0, v0, v6, vcc
	v_cndmask_b32_e64 v1, v1, 6, vcc
	v_cmp_gt_f32_e32 vcc, v7, v0
	s_nop 1
	v_cndmask_b32_e32 v0, v0, v7, vcc
	v_cndmask_b32_e64 v1, v1, 7, vcc
	v_cmp_gt_f32_e32 vcc, v9, v0
	s_nop 1
	v_cndmask_b32_e32 v0, v0, v9, vcc
	v_cndmask_b32_e64 v1, v1, 8, vcc
	v_cmp_gt_f32_e32 vcc, v10, v0
	s_nop 1
	v_cndmask_b32_e32 v0, v0, v10, vcc
	v_cndmask_b32_e64 v1, v1, 9, vcc
	v_cmp_gt_f32_e32 vcc, v11, v0
	s_nop 1
	v_cndmask_b32_e32 v0, v0, v11, vcc
	v_cndmask_b32_e64 v1, v1, 10, vcc
	v_cmp_gt_f32_e32 vcc, v12, v0
	s_nop 1
	v_cndmask_b32_e32 v0, v0, v12, vcc
	v_cndmask_b32_e64 v1, v1, 11, vcc
	v_cmp_gt_f32_e32 vcc, v13, v0
	s_nop 1
	v_cndmask_b32_e32 v0, v0, v13, vcc
	v_cndmask_b32_e64 v1, v1, 12, vcc
	v_cmp_gt_f32_e32 vcc, v14, v0
	s_nop 1
	v_cndmask_b32_e32 v0, v0, v14, vcc
	v_cndmask_b32_e64 v1, v1, 13, vcc
	v_cmp_gt_f32_e32 vcc, v15, v0
	s_nop 1
	v_cndmask_b32_e32 v0, v0, v15, vcc
	v_cndmask_b32_e64 v1, v1, 14, vcc
	v_cmp_ngt_f32_e32 vcc, v8, v0
	s_nop 1
	v_cndmask_b32_e32 v0, 15, v1, vcc
	v_lshlrev_b32_e64 v1, v0, 1
	v_cmp_lt_i32_e32 vcc, -1, v0
	s_nop 1
	v_cndmask_b32_e32 v0, 0, v1, vcc
	v_or3_b32 v0, v24, v23, v0
.LBB0_942:
	s_andn2_saveexec_b64 s[8:9], s[8:9]
	v_mov_b32_e32 v0, 0
	s_or_b64 exec, exec, s[8:9]
	v_readlane_b32 s8, v253, 49
	v_lshlrev_b32_e32 v1, 3, v18
	v_lshlrev_b64 v[14:15], 19, v[16:17]
	v_readlane_b32 s9, v253, 50
	v_lshl_or_b32 v130, v19, 8, v1
	v_lshlrev_b32_e32 v26, 1, v130
	v_lshl_add_u64 v[16:17], s[8:9], 0, v[14:15]
	v_mov_b32_e32 v27, v131
	v_lshl_add_u64 v[134:135], v[16:17], 0, v[26:27]
	global_load_dwordx4 v[2:5], v[134:135], off
	global_load_dwordx4 v[6:9], v[134:135], off offset:1024
	global_load_dwordx4 v[10:13], v[134:135], off offset:2048
	global_load_dwordx4 v[22:25], v[134:135], off offset:3072
	v_readlane_b32 s8, v253, 51
	v_cmp_eq_u32_e32 vcc, 0, v154
	v_readlane_b32 s9, v253, 52
	v_mov_b32_e32 v29, v131
	v_cndmask_b32_e64 v28, v197, 0, vcc
	v_lshl_add_u64 v[14:15], s[8:9], 0, v[14:15]
	v_lshl_add_u64 v[16:17], v[16:17], 0, v[28:29]
	v_lshl_add_u64 v[16:17], v[16:17], 0, v[26:27]
	v_lshl_add_u64 v[136:137], v[14:15], 0, v[130:131]
	global_load_dwordx4 v[108:111], v[16:17], off offset:3072
	global_load_dwordx4 v[104:107], v[16:17], off offset:2048
	global_load_dwordx4 v[100:103], v[16:17], off offset:1024
	global_load_dwordx4 v[96:99], v[16:17], off
	global_load_dwordx2 v[114:115], v[136:137], off offset:3584
	global_load_dwordx2 v[112:113], v[136:137], off offset:3072
	global_load_dwordx2 v[118:119], v[136:137], off offset:2560
	global_load_dwordx2 v[116:117], v[136:137], off offset:2048
	global_load_dwordx2 v[122:123], v[136:137], off offset:1536
	global_load_dwordx2 v[120:121], v[136:137], off offset:1024
	global_load_dwordx2 v[126:127], v[136:137], off offset:512
	global_load_dwordx2 v[124:125], v[136:137], off
	s_mov_b32 s56, 0
	v_lshrrev_b32_e32 v1, 3, v154
	s_mov_b32 s57, s56
	v_lshl_or_b32 v157, 1, v1, v0
	s_mov_b32 s58, s56
	s_mov_b32 s59, s56
	s_mov_b32 s60, s56
	s_mov_b32 s61, s56
	s_mov_b32 s62, s56
	s_mov_b32 s63, s56
	s_mov_b32 s64, s56
	s_mov_b32 s65, s56
	s_mov_b32 s66, s56
	s_mov_b32 s67, s56
	s_mov_b32 s68, s56
	s_mov_b32 s69, s56
	s_mov_b32 s70, s56
	s_mov_b32 s71, s56
	v_sub_u32_e32 v16, 0, v21
	v_lshlrev_b32_e32 v155, 2, v19
	v_lshlrev_b32_e32 v133, 6, v20
	v_lshl_add_u32 v156, v20, 7, 0
	v_sub_u32_e32 v158, v18, v155
	v_lshl_add_u32 v159, v16, 5, v208
	v_mov_b32_e32 v160, 0
	v_mov_b32_e32 v161, 0xff800000
	s_waitcnt vmcnt(15)
	v_mfma_f32_32x32x16_bf16 v[48:63], v[2:5], v[80:83], 0
	s_waitcnt vmcnt(14)
	v_mfma_f32_32x32x16_bf16 v[48:63], v[6:9], v[84:87], v[48:63]
	s_waitcnt vmcnt(13)
	v_mfma_f32_32x32x16_bf16 v[48:63], v[10:13], v[88:91], v[48:63]
	v_mov_b64_e32 v[0:1], s[56:57]
	v_mov_b64_e32 v[14:15], s[70:71]
	v_mov_b64_e32 v[2:3], s[58:59]
	v_mov_b64_e32 v[4:5], s[60:61]
	v_mov_b64_e32 v[6:7], s[62:63]
	v_mov_b64_e32 v[8:9], s[64:65]
	v_mov_b64_e32 v[10:11], s[66:67]
	s_waitcnt vmcnt(12)
; #define MFMA32(a, b, c) __builtin_amdgcn_mfma_f32_32x32x16_bf16((a), (b), (c), 0, 0, 0)
; template <class KP, class VP, class ACT, class FILL>
; DI void attn_loop(AttnSt& st, const bf16x8 (&qf)[4], int k0, int k1, size_t vstride, KP kp, VP vp, ACT act, FILL fill) {
;   KVT cur, nxt;
;   {
;     KVT t0; load_kv(t0, kp(k0), vp(k0), vstride);
; #pragma unroll
;     for (int i = 0; i < 8; ++i) cur.v[i] = t0.v[i];
; #pragma unroll
;     for (int i = 0; i < 4; ++i) cur.k[i] = t0.k[i];
;   }
;   f32x16 s_cur;
;   { const float z = 0.f;
; #pragma unroll
;     for (int i = 0; i < 16; ++i) s_cur[i] = z; }
; #pragma unroll
;   for (int ss = 0; ss < 4; ++ss) s_cur = MFMA32(cur.k[ss], qf[ss], s_cur);
;   {
;     const int kn = (k0 < k1) ? k0 + 1 : k1;
;     const bf16_t* krow = kp(kn);
; #pragma unroll
;     for (int ss = 0; ss < 4; ++ss) nxt.k[ss] = *(const bf16x8*)(krow + 512 * ss);
;   }
; DI void bias16(const unsigned char* blut, const float* tblh, const int (&dist)[16], float (&bv)[16]) {
;   int bk[16];
; #pragma unroll
;   for (int i = 0; i < 16; ++i) { const int d = dist[i] < 0 ? 0 : (dist[i] > 2048 ? 2048 : dist[i]); bk[i] = blut[d]; }
; #pragma unroll
;   for (int i = 0; i < 16; ++i) asm volatile("" : "+v"(bk[i]));
; #pragma unroll
;   for (int i = 0; i < 16; ++i) bv[i] = tblh[bk[i]];
; #pragma unroll
;   for (int i = 0; i < 16; ++i) asm volatile("" : "+v"(bv[i]));
; }
	v_mfma_f32_32x32x16_bf16 v[48:63], v[22:25], v[92:95], v[48:63]
	v_mov_b64_e32 v[12:13], s[68:69]
	v_mov_b64_e32 v[30:31], v[14:15]
	s_mov_b64 s[58:59], 0
	v_mov_b64_e32 v[28:29], v[12:13]
	v_mov_b64_e32 v[26:27], v[10:11]
	v_mov_b64_e32 v[24:25], v[8:9]
	v_mov_b64_e32 v[22:23], v[6:7]
	v_mov_b64_e32 v[20:21], v[4:5]
	v_mov_b64_e32 v[18:19], v[2:3]
	v_mov_b64_e32 v[16:17], v[0:1]
	s_waitcnt vmcnt(0)
	v_readfirstlane_b32 s60, v154
	s_mov_b32 s56, 0
	s_mov_b32 s23, 0
	s_min_u32 s24, s23, s60
	s_lshl_b32 s26, s24, 12
	s_mov_b32 s27, 0
	v_lshl_add_u64 v[186:187], v[134:135], 0, s[26:27]
	global_load_dwordx4 v[96:99], v[186:187], off
	global_load_dwordx4 v[100:103], v[186:187], off offset:1024
	global_load_dwordx4 v[104:107], v[186:187], off offset:2048
	global_load_dwordx4 v[108:111], v[186:187], off offset:3072
	s_mov_b32 s23, 1
	s_min_u32 s24, s23, s60
	s_lshl_b32 s26, s24, 12
	s_mov_b32 s27, 0
	v_lshl_add_u64 v[186:187], v[134:135], 0, s[26:27]
	global_load_dwordx4 v[112:115], v[186:187], off
	global_load_dwordx4 v[116:119], v[186:187], off offset:1024
	global_load_dwordx4 v[120:123], v[186:187], off offset:2048
	global_load_dwordx4 v[124:127], v[186:187], off offset:3072
	s_mov_b32 s23, 0
	s_min_u32 s24, s23, s60
	s_lshl_b32 s26, s24, 12
	s_mov_b32 s27, 0
	v_lshl_add_u64 v[218:219], v[136:137], 0, s[26:27]
	global_load_dwordx2 v[64:65], v[218:219], off
	global_load_dwordx2 v[66:67], v[218:219], off offset:512
	global_load_dwordx2 v[68:69], v[218:219], off offset:1024
	global_load_dwordx2 v[70:71], v[218:219], off offset:1536
	global_load_dwordx2 v[72:73], v[218:219], off offset:2048
	global_load_dwordx2 v[74:75], v[218:219], off offset:2560
	global_load_dwordx2 v[76:77], v[218:219], off offset:3072
	global_load_dwordx2 v[78:79], v[218:219], off offset:3584
	s_mov_b32 s23, 1
	s_min_u32 s24, s23, s60
	s_lshl_b32 s26, s24, 12
	s_mov_b32 s27, 0
	v_lshl_add_u64 v[218:219], v[136:137], 0, s[26:27]
	global_load_dwordx2 v[138:139], v[218:219], off
	global_load_dwordx2 v[140:141], v[218:219], off offset:512
	global_load_dwordx2 v[142:143], v[218:219], off offset:1024
	global_load_dwordx2 v[144:145], v[218:219], off offset:1536
	global_load_dwordx2 v[146:147], v[218:219], off offset:2048
	global_load_dwordx2 v[148:149], v[218:219], off offset:2560
	global_load_dwordx2 v[150:151], v[218:219], off offset:3072
	global_load_dwordx2 v[152:153], v[218:219], off offset:3584
	v_lshrrev_b32_e32 v184, 6, v129
	v_mul_u32_u24_e32 v184, 6912, v184
	v_add_u32_e32 v180, 8192, v184
	v_and_b32_e32 v184, 63, v129
	v_add_u32_e32 v162, -64, v184
	v_mov_b32_e32 v162, 0
	v_mov_b32_e32 v163, v184
	v_add_u32_e32 v164, 64, v184
	v_add_u32_e32 v165, 128, v184
	v_add_u32_e32 v166, 192, v184
	v_add_u32_e32 v167, 256, v184
	v_add_u32_e32 v168, 320, v184
	v_add_u32_e32 v169, 384, v184
	v_add_u32_e32 v170, 448, v184
	ds_read_u8 v162, v162
	ds_read_u8 v163, v163
	ds_read_u8 v164, v164
	ds_read_u8 v165, v165
	ds_read_u8 v166, v166
	ds_read_u8 v167, v167
	ds_read_u8 v168, v168
	ds_read_u8 v169, v169
	ds_read_u8 v170, v170
	s_waitcnt lgkmcnt(8)
	v_lshl_add_u32 v162, v162, 2, v156
	s_waitcnt lgkmcnt(7)
	v_lshl_add_u32 v163, v163, 2, v156
	s_waitcnt lgkmcnt(6)
	v_lshl_add_u32 v164, v164, 2, v156
	s_waitcnt lgkmcnt(5)
	v_lshl_add_u32 v165, v165, 2, v156
	s_waitcnt lgkmcnt(4)
	v_lshl_add_u32 v166, v166, 2, v156
	s_waitcnt lgkmcnt(3)
	v_lshl_add_u32 v167, v167, 2, v156
	s_waitcnt lgkmcnt(2)
	v_lshl_add_u32 v168, v168, 2, v156
	s_waitcnt lgkmcnt(1)
	v_lshl_add_u32 v169, v169, 2, v156
	s_waitcnt lgkmcnt(0)
	v_lshl_add_u32 v170, v170, 2, v156
	ds_read_b32 v162, v162 offset:4864
	ds_read_b32 v163, v163 offset:4864
	ds_read_b32 v164, v164 offset:4864
	ds_read_b32 v165, v165 offset:4864
	ds_read_b32 v166, v166 offset:4864
	ds_read_b32 v167, v167 offset:4864
	ds_read_b32 v168, v168 offset:4864
	ds_read_b32 v169, v169 offset:4864
	ds_read_b32 v170, v170 offset:4864
	v_lshl_add_u32 v182, v184, 2, v180
	s_waitcnt lgkmcnt(8)
	ds_write_b32 v182, v162 offset:0
	s_waitcnt lgkmcnt(7)
	ds_write_b32 v182, v163 offset:256
	s_waitcnt lgkmcnt(6)
	ds_write_b32 v182, v164 offset:512
	s_waitcnt lgkmcnt(5)
	ds_write_b32 v182, v165 offset:768
	s_waitcnt lgkmcnt(4)
	ds_write_b32 v182, v166 offset:1024
	s_waitcnt lgkmcnt(3)
	ds_write_b32 v182, v167 offset:1280
	s_waitcnt lgkmcnt(2)
	ds_write_b32 v182, v168 offset:1536
	s_waitcnt lgkmcnt(1)
	ds_write_b32 v182, v169 offset:1792
	s_waitcnt lgkmcnt(0)
	ds_write_b32 v182, v170 offset:2048
	v_add_u32_e32 v162, 512, v184
	v_add_u32_e32 v163, 576, v184
	v_add_u32_e32 v164, 640, v184
	v_add_u32_e32 v165, 704, v184
	v_add_u32_e32 v166, 768, v184
	v_add_u32_e32 v167, 832, v184
	v_add_u32_e32 v168, 896, v184
	v_add_u32_e32 v169, 960, v184
	v_add_u32_e32 v170, 1024, v184
	ds_read_u8 v162, v162
	ds_read_u8 v163, v163
	ds_read_u8 v164, v164
	ds_read_u8 v165, v165
	ds_read_u8 v166, v166
	ds_read_u8 v167, v167
	ds_read_u8 v168, v168
	ds_read_u8 v169, v169
	ds_read_u8 v170, v170
	s_waitcnt lgkmcnt(8)
	v_lshl_add_u32 v162, v162, 2, v156
	s_waitcnt lgkmcnt(7)
	v_lshl_add_u32 v163, v163, 2, v156
	s_waitcnt lgkmcnt(6)
	v_lshl_add_u32 v164, v164, 2, v156
	s_waitcnt lgkmcnt(5)
	v_lshl_add_u32 v165, v165, 2, v156
	s_waitcnt lgkmcnt(4)
	v_lshl_add_u32 v166, v166, 2, v156
	s_waitcnt lgkmcnt(3)
	v_lshl_add_u32 v167, v167, 2, v156
	s_waitcnt lgkmcnt(2)
	v_lshl_add_u32 v168, v168, 2, v156
	s_waitcnt lgkmcnt(1)
	v_lshl_add_u32 v169, v169, 2, v156
	s_waitcnt lgkmcnt(0)
	v_lshl_add_u32 v170, v170, 2, v156
	ds_read_b32 v162, v162 offset:4864
	ds_read_b32 v163, v163 offset:4864
	ds_read_b32 v164, v164 offset:4864
	ds_read_b32 v165, v165 offset:4864
	ds_read_b32 v166, v166 offset:4864
	ds_read_b32 v167, v167 offset:4864
	ds_read_b32 v168, v168 offset:4864
	ds_read_b32 v169, v169 offset:4864
	ds_read_b32 v170, v170 offset:4864
	v_lshl_add_u32 v182, v184, 2, v180
	s_waitcnt lgkmcnt(8)
; DI void bias16(const unsigned char* blut, const float* tblh, const int (&dist)[16], float (&bv)[16]) {
;   int bk[16];
; #pragma unroll
;   for (int i = 0; i < 16; ++i) { const int d = dist[i] < 0 ? 0 : (dist[i] > 2048 ? 2048 : dist[i]); bk[i] = blut[d]; }
; #pragma unroll
;   for (int i = 0; i < 16; ++i) asm volatile("" : "+v"(bk[i]));
; #pragma unroll
;   for (int i = 0; i < 16; ++i) bv[i] = tblh[bk[i]];
; #pragma unroll
;   for (int i = 0; i < 16; ++i) asm volatile("" : "+v"(bv[i]));
; }
; DI void moba_item(const Params& p, int b, int hd, int qb, const unsigned char* blut, const float* tbl) {
;     ...
;         const float b31 = tblh[31];
	ds_write_b32 v182, v162 offset:2304
	s_waitcnt lgkmcnt(7)
	ds_write_b32 v182, v163 offset:2560
	s_waitcnt lgkmcnt(6)
	ds_write_b32 v182, v164 offset:2816
	s_waitcnt lgkmcnt(5)
	ds_write_b32 v182, v165 offset:3072
	s_waitcnt lgkmcnt(4)
	ds_write_b32 v182, v166 offset:3328
	s_waitcnt lgkmcnt(3)
	ds_write_b32 v182, v167 offset:3584
	s_waitcnt lgkmcnt(2)
	ds_write_b32 v182, v168 offset:3840
	s_waitcnt lgkmcnt(1)
	ds_write_b32 v182, v169 offset:4096
	s_waitcnt lgkmcnt(0)
	ds_write_b32 v182, v170 offset:4352
	v_add_u32_e32 v162, 1088, v184
	v_add_u32_e32 v163, 1152, v184
	v_add_u32_e32 v164, 1216, v184
	v_add_u32_e32 v165, 1280, v184
	v_add_u32_e32 v166, 1344, v184
	v_add_u32_e32 v167, 1408, v184
	v_add_u32_e32 v168, 1472, v184
	v_add_u32_e32 v169, 1536, v184
	v_add_u32_e32 v170, 1600, v184
	ds_read_u8 v162, v162
	ds_read_u8 v163, v163
	ds_read_u8 v164, v164
	ds_read_u8 v165, v165
	ds_read_u8 v166, v166
	ds_read_u8 v167, v167
	ds_read_u8 v168, v168
	ds_read_u8 v169, v169
	ds_read_u8 v170, v170
	s_waitcnt lgkmcnt(8)
	v_lshl_add_u32 v162, v162, 2, v156
	s_waitcnt lgkmcnt(7)
	v_lshl_add_u32 v163, v163, 2, v156
	s_waitcnt lgkmcnt(6)
	v_lshl_add_u32 v164, v164, 2, v156
	s_waitcnt lgkmcnt(5)
	v_lshl_add_u32 v165, v165, 2, v156
	s_waitcnt lgkmcnt(4)
	v_lshl_add_u32 v166, v166, 2, v156
	s_waitcnt lgkmcnt(3)
	v_lshl_add_u32 v167, v167, 2, v156
	s_waitcnt lgkmcnt(2)
	v_lshl_add_u32 v168, v168, 2, v156
	s_waitcnt lgkmcnt(1)
	v_lshl_add_u32 v169, v169, 2, v156
	s_waitcnt lgkmcnt(0)
	v_lshl_add_u32 v170, v170, 2, v156
	ds_read_b32 v162, v162 offset:4864
	ds_read_b32 v163, v163 offset:4864
	ds_read_b32 v164, v164 offset:4864
	ds_read_b32 v165, v165 offset:4864
	ds_read_b32 v166, v166 offset:4864
	ds_read_b32 v167, v167 offset:4864
	ds_read_b32 v168, v168 offset:4864
	ds_read_b32 v169, v169 offset:4864
	ds_read_b32 v170, v170 offset:4864
	v_lshl_add_u32 v182, v184, 2, v180
	s_waitcnt lgkmcnt(8)
	ds_write_b32 v182, v162 offset:4608
	s_waitcnt lgkmcnt(7)
	ds_write_b32 v182, v163 offset:4864
	s_waitcnt lgkmcnt(6)
	ds_write_b32 v182, v164 offset:5120
	s_waitcnt lgkmcnt(5)
	ds_write_b32 v182, v165 offset:5376
	s_waitcnt lgkmcnt(4)
	ds_write_b32 v182, v166 offset:5632
	s_waitcnt lgkmcnt(3)
	ds_write_b32 v182, v167 offset:5888
	s_waitcnt lgkmcnt(2)
	ds_write_b32 v182, v168 offset:6144
	s_waitcnt lgkmcnt(1)
	ds_write_b32 v182, v169 offset:6400
	s_waitcnt lgkmcnt(0)
	ds_write_b32 v182, v170 offset:6656
	ds_read_b32 v178, v156 offset:4988
	v_add_u32_e32 v180, 148, v180
	v_mov_b32_e32 v181, 0x7f800000
	s_waitcnt lgkmcnt(0)
; #define MFMA32(a, b, c) __builtin_amdgcn_mfma_f32_32x32x16_bf16((a), (b), (c), 0, 0, 0)
; #define NEGINF (-__builtin_inff())
; DI int crow(int i, int h) { return (i & 3) + 8 * (i >> 2) + 4 * h; }
; template <class KP, class VP, class ACT, class FILL>
; DI void attn_loop(AttnSt& st, const bf16x8 (&qf)[4], int k0, int k1, size_t vstride, KP kp, VP vp, ACT act, FILL fill) {
;     ...
;   for (int kt = k0; kt <= k1; ++kt) {
;     const int kn = (kt < k1) ? kt + 1 : k1;
;     const int kn2 = (kt + 2 <= k1) ? kt + 2 : k1;
;     {
;       const bf16_t* v0 = vp(kn);
; #pragma unroll
;       for (int j = 0; j < 8; ++j) nxt.v[j] = *(const s16x4*)(v0 + 256 * j);
;     }
;     bf16x8 k2[4];
;     {
;       const bf16_t* krow = kp(kn2);
; #pragma unroll
;       for (int ss = 0; ss < 4; ++ss) k2[ss] = *(const bf16x8*)(krow + 512 * ss);
;     }
;     f32x16 s_next;
; #pragma unroll
;     for (int i = 0; i < 16; ++i) s_next[i] = 0.f;
; #pragma unroll
;     for (int ss = 0; ss < 4; ++ss) s_next = MFMA32(nxt.k[ss], qf[ss], s_next);
; DI void moba_item(const Params& p, int b, int hd, int qb, const unsigned char* blut, const float* tbl) {
;     ...
;     [&](int kt, const f32x16& s, float (&lg)[16]) {
;       const bool bs = (mmask >> (kt >> 3)) & 1u;
;       if (qb * 32 - (kt * 32 + 31) >= 1513) {
;         const float b31 = tblh[31];
; #pragma unroll
;         for (int i = 0; i < 16; ++i) lg[i] = bs ? s[i] + b31 : NEGINF;
;       } else {
;         int dist[16]; float bv[16];
; #pragma unroll
;         for (int i = 0; i < 16; ++i) dist[i] = t - (kt * 32 + crow(i, h));
;         bias16(blut, tblh, dist, bv);
; #pragma unroll
;         for (int i = 0; i < 16; ++i) lg[i] = (bs && dist[i] >= 0) ? s[i] + bv[i] : NEGINF;
;       }
;     });
.Lamoba_loop:
	s_waitcnt vmcnt(16)
	v_mfma_f32_32x32x16_bf16 v[32:47], v[96:99], v[80:83], 0
	v_mfma_f32_32x32x16_bf16 v[48:63], v[112:115], v[80:83], 0
	v_mfma_f32_32x32x16_bf16 v[32:47], v[100:103], v[84:87], v[32:47]
	v_mfma_f32_32x32x16_bf16 v[48:63], v[116:119], v[84:87], v[48:63]
	v_mfma_f32_32x32x16_bf16 v[32:47], v[104:107], v[88:91], v[32:47]
	v_mfma_f32_32x32x16_bf16 v[48:63], v[120:123], v[88:91], v[48:63]
	v_mfma_f32_32x32x16_bf16 v[32:47], v[108:111], v[92:95], v[32:47]
	v_mfma_f32_32x32x16_bf16 v[48:63], v[124:127], v[92:95], v[48:63]
	s_add_u32 s23, s56, 2
	s_min_u32 s24, s23, s60
	s_lshl_b32 s26, s24, 12
	s_mov_b32 s27, 0
	v_lshl_add_u64 v[186:187], v[134:135], 0, s[26:27]
	global_load_dwordx4 v[96:99], v[186:187], off
	global_load_dwordx4 v[100:103], v[186:187], off offset:1024
	global_load_dwordx4 v[104:107], v[186:187], off offset:2048
	global_load_dwordx4 v[108:111], v[186:187], off offset:3072
	s_add_u32 s23, s56, 3
	s_min_u32 s24, s23, s60
	s_lshl_b32 s26, s24, 12
	s_mov_b32 s27, 0
	v_lshl_add_u64 v[186:187], v[134:135], 0, s[26:27]
	global_load_dwordx4 v[112:115], v[186:187], off
	global_load_dwordx4 v[116:119], v[186:187], off offset:1024
	global_load_dwordx4 v[120:123], v[186:187], off offset:2048
	global_load_dwordx4 v[124:127], v[186:187], off offset:3072
	s_sub_i32 s61, s60, s56
	s_lshr_b32 s23, s56, 3
	v_bfe_u32 v184, v157, s23, 1
	v_cmp_eq_u32_e64 s[62:63], 1, v184
	s_cmp_ge_i32 s61, 50
	s_cbranch_scc1 .Lamoba_far
	s_lshl_b32 s23, s61, 5
	v_add_u32_e32 v179, s23, v158
	v_lshl_add_u32 v182, v179, 2, v180
	v_subrev_u32_e32 v183, 128, v182
	ds_read_b32 v162, v182 offset:108
	ds_read_b32 v163, v182 offset:104
	ds_read_b32 v164, v182 offset:100
	ds_read_b32 v165, v182 offset:96
	ds_read_b32 v166, v182 offset:76
	ds_read_b32 v167, v182 offset:72
	ds_read_b32 v168, v182 offset:68
	ds_read_b32 v169, v182 offset:64
	ds_read_b32 v170, v182 offset:44
	ds_read_b32 v171, v182 offset:40
	ds_read_b32 v172, v182 offset:36
	ds_read_b32 v173, v182 offset:32
	ds_read_b32 v174, v182 offset:12
	ds_read_b32 v175, v182 offset:8
	ds_read_b32 v176, v182 offset:4
	ds_read_b32 v177, v182 offset:0
	s_waitcnt lgkmcnt(8)
	v_add_f32_e32 v32, v32, v162
	v_add_f32_e32 v33, v33, v163
	v_add_f32_e32 v34, v34, v164
	v_add_f32_e32 v35, v35, v165
	v_add_f32_e32 v36, v36, v166
	v_add_f32_e32 v37, v37, v167
	v_add_f32_e32 v38, v38, v168
	v_add_f32_e32 v39, v39, v169
	s_waitcnt lgkmcnt(0)
	v_add_f32_e32 v40, v40, v170
	v_add_f32_e32 v41, v41, v171
	v_add_f32_e32 v42, v42, v172
	v_add_f32_e32 v43, v43, v173
	v_add_f32_e32 v44, v44, v174
	v_add_f32_e32 v45, v45, v175
	v_add_f32_e32 v46, v46, v176
	v_add_f32_e32 v47, v47, v177
	ds_read_b32 v162, v183 offset:108
	ds_read_b32 v163, v183 offset:104
	ds_read_b32 v164, v183 offset:100
	ds_read_b32 v165, v183 offset:96
	ds_read_b32 v166, v183 offset:76
	ds_read_b32 v167, v183 offset:72
	ds_read_b32 v168, v183 offset:68
	ds_read_b32 v169, v183 offset:64
	ds_read_b32 v170, v183 offset:44
	ds_read_b32 v171, v183 offset:40
	ds_read_b32 v172, v183 offset:36
	ds_read_b32 v173, v183 offset:32
	ds_read_b32 v174, v183 offset:12
	ds_read_b32 v175, v183 offset:8
	ds_read_b32 v176, v183 offset:4
	ds_read_b32 v177, v183 offset:0
	s_waitcnt lgkmcnt(8)
	v_add_f32_e32 v48, v48, v162
	v_add_f32_e32 v49, v49, v163
	v_add_f32_e32 v50, v50, v164
	v_add_f32_e32 v51, v51, v165
	v_add_f32_e32 v52, v52, v166
	v_add_f32_e32 v53, v53, v167
	v_add_f32_e32 v54, v54, v168
	v_add_f32_e32 v55, v55, v169
	s_waitcnt lgkmcnt(0)
	v_add_f32_e32 v56, v56, v170
	v_add_f32_e32 v57, v57, v171
	v_add_f32_e32 v58, v58, v172
	v_add_f32_e32 v59, v59, v173
	v_add_f32_e32 v60, v60, v174
	v_add_f32_e32 v61, v61, v175
	v_add_f32_e32 v62, v62, v176
	v_add_f32_e32 v63, v63, v177
	s_cmp_ge_i32 s61, 2
	s_cbranch_scc1 .Lamoba_softmax
	v_subrev_u32_e32 v184, 32, v179
	v_cmp_le_i32_e32 vcc, 0, v179
	s_nop 1
	v_cndmask_b32_e32 v32, v199, v32, vcc
	v_cmp_le_i32_e32 vcc, 1, v179
	s_nop 1
	v_cndmask_b32_e32 v33, v199, v33, vcc
	v_cmp_le_i32_e32 vcc, 2, v179
	s_nop 1
	v_cndmask_b32_e32 v34, v199, v34, vcc
	v_cmp_le_i32_e32 vcc, 3, v179
	s_nop 1
	v_cndmask_b32_e32 v35, v199, v35, vcc
	v_cmp_le_i32_e32 vcc, 8, v179
	s_nop 1
	v_cndmask_b32_e32 v36, v199, v36, vcc
	v_cmp_le_i32_e32 vcc, 9, v179
	s_nop 1
	v_cndmask_b32_e32 v37, v199, v37, vcc
	v_cmp_le_i32_e32 vcc, 10, v179
	s_nop 1
	v_cndmask_b32_e32 v38, v199, v38, vcc
	v_cmp_le_i32_e32 vcc, 11, v179
	s_nop 1
	v_cndmask_b32_e32 v39, v199, v39, vcc
	v_cmp_le_i32_e32 vcc, 16, v179
	s_nop 1
	v_cndmask_b32_e32 v40, v199, v40, vcc
	v_cmp_le_i32_e32 vcc, 17, v179
	s_nop 1
	v_cndmask_b32_e32 v41, v199, v41, vcc
	v_cmp_le_i32_e32 vcc, 18, v179
	s_nop 1
	v_cndmask_b32_e32 v42, v199, v42, vcc
	v_cmp_le_i32_e32 vcc, 19, v179
	s_nop 1
	v_cndmask_b32_e32 v43, v199, v43, vcc
	v_cmp_le_i32_e32 vcc, 24, v179
	s_nop 1
	v_cndmask_b32_e32 v44, v199, v44, vcc
	v_cmp_le_i32_e32 vcc, 25, v179
	s_nop 1
	v_cndmask_b32_e32 v45, v199, v45, vcc
	v_cmp_le_i32_e32 vcc, 26, v179
	s_nop 1
	v_cndmask_b32_e32 v46, v199, v46, vcc
	v_cmp_le_i32_e32 vcc, 27, v179
	s_nop 1
	v_cndmask_b32_e32 v47, v199, v47, vcc
	v_cmp_le_i32_e32 vcc, 0, v184
	s_nop 1
	v_cndmask_b32_e32 v48, v199, v48, vcc
	v_cmp_le_i32_e32 vcc, 1, v184
	s_nop 1
	v_cndmask_b32_e32 v49, v199, v49, vcc
	v_cmp_le_i32_e32 vcc, 2, v184
	s_nop 1
	v_cndmask_b32_e32 v50, v199, v50, vcc
	v_cmp_le_i32_e32 vcc, 3, v184
	s_nop 1
	v_cndmask_b32_e32 v51, v199, v51, vcc
	v_cmp_le_i32_e32 vcc, 8, v184
	s_nop 1
	v_cndmask_b32_e32 v52, v199, v52, vcc
	v_cmp_le_i32_e32 vcc, 9, v184
	s_nop 1
	v_cndmask_b32_e32 v53, v199, v53, vcc
	v_cmp_le_i32_e32 vcc, 10, v184
	s_nop 1
	v_cndmask_b32_e32 v54, v199, v54, vcc
	v_cmp_le_i32_e32 vcc, 11, v184
	s_nop 1
	v_cndmask_b32_e32 v55, v199, v55, vcc
	v_cmp_le_i32_e32 vcc, 16, v184
	s_nop 1
	v_cndmask_b32_e32 v56, v199, v56, vcc
	v_cmp_le_i32_e32 vcc, 17, v184
	s_nop 1
	v_cndmask_b32_e32 v57, v199, v57, vcc
	v_cmp_le_i32_e32 vcc, 18, v184
	s_nop 1
	v_cndmask_b32_e32 v58, v199, v58, vcc
	v_cmp_le_i32_e32 vcc, 19, v184
	s_nop 1
	v_cndmask_b32_e32 v59, v199, v59, vcc
	v_cmp_le_i32_e32 vcc, 24, v184
	s_nop 1
	v_cndmask_b32_e32 v60, v199, v60, vcc
	v_cmp_le_i32_e32 vcc, 25, v184
	s_nop 1
	v_cndmask_b32_e32 v61, v199, v61, vcc
	v_cmp_le_i32_e32 vcc, 26, v184
	s_nop 1
	v_cndmask_b32_e32 v62, v199, v62, vcc
	v_cmp_le_i32_e32 vcc, 27, v184
	s_nop 1
	v_cndmask_b32_e32 v63, v199, v63, vcc
	s_branch .Lamoba_softmax

; #define NEGINF (-__builtin_inff())
; DI float shx32(float v) { const auto r = __builtin_amdgcn_permlane32_swap(__float_as_uint(v), __float_as_uint(v), false, false); return __uint_as_float((threadIdx.x & 32) ? r[0] : r[1]); }
; DI float ex2(float x) { return __builtin_amdgcn_exp2f(x); }
; DI void softmax_step_r(AttnSt& st, const float (&lg)[16], const KVT& t) {
;   float mx = NEGINF;
; #pragma unroll
;   for (int i = 0; i < 16; ++i) mx = fmaxf(mx, lg[i]);
;   mx = fmaxf(mx, shx32(mx));
;   if (__ballot(mx > NEGINF) == 0ull) return;
;   const float mnew = fmaxf(st.m, mx);
;   const float muse = (mnew == NEGINF) ? 0.f : mnew;
;   const float alpha = ex2(st.m - muse);
;   float pr[16]; float rs = 0.f;
; #pragma unroll
;   for (int i = 0; i < 16; ++i) { pr[i] = ex2(lg[i] - muse); rs += pr[i]; }
;   st.l = st.l * alpha + rs;
;   if (__ballot(mnew != st.m) != 0ull) {
; #pragma unroll
;     for (int i = 0; i < 16; ++i) { st.o0[i] *= alpha; st.o1[i] *= alpha; }
;   }
;   st.m = mnew;
.Lamoba_softmax:
	v_max3_f32 v162, v32, v33, v34
	v_max3_f32 v163, v40, v41, v42
	v_max3_f32 v164, v48, v49, v50
	v_max3_f32 v165, v56, v57, v58
	v_max3_f32 v162, v162, v35, v36
	v_max3_f32 v163, v163, v43, v44
	v_max3_f32 v164, v164, v51, v52
	v_max3_f32 v165, v165, v59, v60
	v_max3_f32 v162, v162, v37, v38
	v_max3_f32 v163, v163, v45, v46
	v_max3_f32 v164, v164, v53, v54
	v_max3_f32 v165, v165, v61, v62
	v_max_f32_e32 v162, v162, v39
	v_max_f32_e32 v163, v163, v47
	v_max_f32_e32 v164, v164, v55
	v_max_f32_e32 v165, v165, v63
	v_max3_f32 v162, v162, v163, v164
	v_max_f32_e32 v162, v162, v165
	v_mov_b32_e32 v163, v162
	v_mov_b32_e32 v164, v162
	s_nop 1
	v_permlane32_swap_b32_e32 v163, v164
	v_cndmask_b32_e64 v163, v163, v164, s[12:13]
	v_max_f32_e32 v162, v162, v163
	v_cndmask_b32_e64 v162, v199, v162, s[62:63]
	v_max_f32_e32 v163, v161, v162
	v_cmp_neq_f32_e32 vcc, v199, v163
	s_nop 1
	v_cndmask_b32_e32 v164, 0, v163, vcc
	v_sub_f32_e32 v165, v161, v164
	v_exp_f32_e32 v165, v165
	v_cndmask_b32_e64 v164, v181, v164, s[62:63]
	v_cmp_neq_f32_e32 vcc, v161, v163
	v_mov_b32_e32 v161, v163
	v_sub_f32_e32 v32, v32, v164
	v_sub_f32_e32 v33, v33, v164
	v_sub_f32_e32 v34, v34, v164
	v_sub_f32_e32 v35, v35, v164
	v_sub_f32_e32 v36, v36, v164
	v_sub_f32_e32 v37, v37, v164
	v_sub_f32_e32 v38, v38, v164
	v_sub_f32_e32 v39, v39, v164
	v_sub_f32_e32 v40, v40, v164
	v_sub_f32_e32 v41, v41, v164
	v_sub_f32_e32 v42, v42, v164
	v_sub_f32_e32 v43, v43, v164
	v_sub_f32_e32 v44, v44, v164
	v_sub_f32_e32 v45, v45, v164
	v_sub_f32_e32 v46, v46, v164
	v_sub_f32_e32 v47, v47, v164
	v_sub_f32_e32 v48, v48, v164
	v_sub_f32_e32 v49, v49, v164
	v_sub_f32_e32 v50, v50, v164
	v_sub_f32_e32 v51, v51, v164
	v_sub_f32_e32 v52, v52, v164
	v_sub_f32_e32 v53, v53, v164
	v_sub_f32_e32 v54, v54, v164
	v_sub_f32_e32 v55, v55, v164
	v_sub_f32_e32 v56, v56, v164
	v_sub_f32_e32 v57, v57, v164
	v_sub_f32_e32 v58, v58, v164
	v_sub_f32_e32 v59, v59, v164
	v_sub_f32_e32 v60, v60, v164
	v_sub_f32_e32 v61, v61, v164
	v_sub_f32_e32 v62, v62, v164
	v_sub_f32_e32 v63, v63, v164
	v_exp_f32_e32 v32, v32
	v_exp_f32_e32 v33, v33
	v_exp_f32_e32 v34, v34
	v_exp_f32_e32 v35, v35
	v_exp_f32_e32 v36, v36
	v_exp_f32_e32 v37, v37
	v_exp_f32_e32 v38, v38
	v_exp_f32_e32 v39, v39
	v_exp_f32_e32 v40, v40
	v_exp_f32_e32 v41, v41
	v_exp_f32_e32 v42, v42
	v_exp_f32_e32 v43, v43
	v_exp_f32_e32 v44, v44
	v_exp_f32_e32 v45, v45
	v_exp_f32_e32 v46, v46
	v_exp_f32_e32 v47, v47
	v_exp_f32_e32 v48, v48
	v_exp_f32_e32 v49, v49
	v_exp_f32_e32 v50, v50
	v_exp_f32_e32 v51, v51
	v_exp_f32_e32 v52, v52
	v_exp_f32_e32 v53, v53
	v_exp_f32_e32 v54, v54
	v_exp_f32_e32 v55, v55
	v_exp_f32_e32 v56, v56
	v_exp_f32_e32 v57, v57
	v_exp_f32_e32 v58, v58
	v_exp_f32_e32 v59, v59
	v_exp_f32_e32 v60, v60
	v_exp_f32_e32 v61, v61
	v_exp_f32_e32 v62, v62
	v_exp_f32_e32 v63, v63
	v_add_f32_e32 v166, v32, v33
	v_add_f32_e32 v167, v40, v41
	v_add_f32_e32 v168, v48, v49
	v_add_f32_e32 v169, v56, v57
	v_add_f32_e32 v166, v166, v34
	v_add_f32_e32 v167, v167, v42
	v_add_f32_e32 v168, v168, v50
	v_add_f32_e32 v169, v169, v58
	v_add_f32_e32 v166, v166, v35
	v_add_f32_e32 v167, v167, v43
	v_add_f32_e32 v168, v168, v51
	v_add_f32_e32 v169, v169, v59
	v_add_f32_e32 v166, v166, v36
	v_add_f32_e32 v167, v167, v44
	v_add_f32_e32 v168, v168, v52
	v_add_f32_e32 v169, v169, v60
	v_add_f32_e32 v166, v166, v37
	v_add_f32_e32 v167, v167, v45
	v_add_f32_e32 v168, v168, v53
	v_add_f32_e32 v169, v169, v61
	v_add_f32_e32 v166, v166, v38
	v_add_f32_e32 v167, v167, v46
	v_add_f32_e32 v168, v168, v54
	v_add_f32_e32 v169, v169, v62
	v_add_f32_e32 v166, v166, v39
	v_add_f32_e32 v167, v167, v47
	v_add_f32_e32 v168, v168, v55
	v_add_f32_e32 v169, v169, v63
	v_add_f32_e32 v166, v166, v167
	v_add_f32_e32 v168, v168, v169
	v_add_f32_e32 v166, v166, v168
	v_fma_f32 v160, v160, v165, v166
	s_cbranch_vccz .Lamoba_noscale
	v_mul_f32_e32 v0, v165, v0
	v_mul_f32_e32 v1, v165, v1
	v_mul_f32_e32 v2, v165, v2
	v_mul_f32_e32 v3, v165, v3
	v_mul_f32_e32 v4, v165, v4
	v_mul_f32_e32 v5, v165, v5
	v_mul_f32_e32 v6, v165, v6
	v_mul_f32_e32 v7, v165, v7
	v_mul_f32_e32 v8, v165, v8
	v_mul_f32_e32 v9, v165, v9
	v_mul_f32_e32 v10, v165, v10
	v_mul_f32_e32 v11, v165, v11
	v_mul_f32_e32 v12, v165, v12
	v_mul_f32_e32 v13, v165, v13
	v_mul_f32_e32 v14, v165, v14
	v_mul_f32_e32 v15, v165, v15
	v_mul_f32_e32 v16, v165, v16
	v_mul_f32_e32 v17, v165, v17
	v_mul_f32_e32 v18, v165, v18
	v_mul_f32_e32 v19, v165, v19
	v_mul_f32_e32 v20, v165, v20
	v_mul_f32_e32 v21, v165, v21
	v_mul_f32_e32 v22, v165, v22
	v_mul_f32_e32 v23, v165, v23
	v_mul_f32_e32 v24, v165, v24
	v_mul_f32_e32 v25, v165, v25
	v_mul_f32_e32 v26, v165, v26
	v_mul_f32_e32 v27, v165, v27
	v_mul_f32_e32 v28, v165, v28
	v_mul_f32_e32 v29, v165, v29
	v_mul_f32_e32 v30, v165, v30
	v_mul_f32_e32 v31, v165, v31
; #define MFMA32(a, b, c) __builtin_amdgcn_mfma_f32_32x32x16_bf16((a), (b), (c), 0, 0, 0)
; DI unsigned pack2(float a, float b) { unsigned r; asm("v_cvt_pk_bf16_f32 %0, %1, %2" : "=v"(r) : "v"(a), "v"(b)); return r; }
; DI void softmax_step_r(AttnSt& st, const float (&lg)[16], const KVT& t) {
;     ...
;   for (int s2 = 0; s2 < 2; ++s2) {
;     u32x4 pk; pk.x = pack2(pr[8 * s2], pr[8 * s2 + 1]); pk.y = pack2(pr[8 * s2 + 2], pr[8 * s2 + 3]); pk.z = pack2(pr[8 * s2 + 4], pr[8 * s2 + 5]); pk.w = pack2(pr[8 * s2 + 6], pr[8 * s2 + 7]);
;     const bf16x8 pb = __builtin_bit_cast(bf16x8, pk);
;     const bf16x8 va0 = __builtin_shufflevector(t.v[s2 * 4 + 0], t.v[s2 * 4 + 1], 0, 1, 2, 3, 4, 5, 6, 7);
;     st.o0 = MFMA32(va0, pb, st.o0);
;     const bf16x8 va1 = __builtin_shufflevector(t.v[s2 * 4 + 2], t.v[s2 * 4 + 3], 0, 1, 2, 3, 4, 5, 6, 7);
;     st.o1 = MFMA32(va1, pb, st.o1);
;   }
; template <class KP, class VP, class ACT, class FILL>
; DI void attn_loop(AttnSt& st, const bf16x8 (&qf)[4], int k0, int k1, size_t vstride, KP kp, VP vp, ACT act, FILL fill) {
;     ...
;   for (int kt = k0; kt <= k1; ++kt) {
;     const int kn = (kt < k1) ? kt + 1 : k1;
;     const int kn2 = (kt + 2 <= k1) ? kt + 2 : k1;
;     {
;       const bf16_t* v0 = vp(kn);
; #pragma unroll
;       for (int j = 0; j < 8; ++j) nxt.v[j] = *(const s16x4*)(v0 + 256 * j);
;     }
.Lamoba_noscale:
	v_cvt_pk_bf16_f32 v162, v32, v33
	v_cvt_pk_bf16_f32 v163, v34, v35
	v_cvt_pk_bf16_f32 v164, v36, v37
	v_cvt_pk_bf16_f32 v165, v38, v39
	v_cvt_pk_bf16_f32 v166, v40, v41
	v_cvt_pk_bf16_f32 v167, v42, v43
	v_cvt_pk_bf16_f32 v168, v44, v45
	v_cvt_pk_bf16_f32 v169, v46, v47
	v_cvt_pk_bf16_f32 v170, v48, v49
	v_cvt_pk_bf16_f32 v171, v50, v51
	v_cvt_pk_bf16_f32 v172, v52, v53
	v_cvt_pk_bf16_f32 v173, v54, v55
	v_cvt_pk_bf16_f32 v174, v56, v57
	v_cvt_pk_bf16_f32 v175, v58, v59
	v_cvt_pk_bf16_f32 v176, v60, v61
	v_cvt_pk_bf16_f32 v177, v62, v63
	s_waitcnt vmcnt(8)
	s_nop 1
	v_mfma_f32_32x32x16_bf16 v[0:15], v[64:67], v[162:165], v[0:15]
	v_mfma_f32_32x32x16_bf16 v[16:31], v[68:71], v[162:165], v[16:31]
	v_mfma_f32_32x32x16_bf16 v[0:15], v[72:75], v[166:169], v[0:15]
	v_mfma_f32_32x32x16_bf16 v[16:31], v[76:79], v[166:169], v[16:31]
	v_mfma_f32_32x32x16_bf16 v[0:15], v[138:141], v[170:173], v[0:15]
	v_mfma_f32_32x32x16_bf16 v[16:31], v[142:145], v[170:173], v[16:31]
	v_mfma_f32_32x32x16_bf16 v[0:15], v[146:149], v[174:177], v[0:15]
	v_mfma_f32_32x32x16_bf16 v[16:31], v[150:153], v[174:177], v[16:31]
	s_add_u32 s23, s56, 2
	s_min_u32 s24, s23, s60
	s_lshl_b32 s26, s24, 12
	s_mov_b32 s27, 0
	v_lshl_add_u64 v[218:219], v[136:137], 0, s[26:27]
	global_load_dwordx2 v[64:65], v[218:219], off
	global_load_dwordx2 v[66:67], v[218:219], off offset:512
	global_load_dwordx2 v[68:69], v[218:219], off offset:1024
	global_load_dwordx2 v[70:71], v[218:219], off offset:1536
	global_load_dwordx2 v[72:73], v[218:219], off offset:2048
	global_load_dwordx2 v[74:75], v[218:219], off offset:2560
	global_load_dwordx2 v[76:77], v[218:219], off offset:3072
	global_load_dwordx2 v[78:79], v[218:219], off offset:3584
	s_add_u32 s23, s56, 3
	s_min_u32 s24, s23, s60
	s_lshl_b32 s26, s24, 12
	s_mov_b32 s27, 0
	v_lshl_add_u64 v[218:219], v[136:137], 0, s[26:27]
	global_load_dwordx2 v[138:139], v[218:219], off
	global_load_dwordx2 v[140:141], v[218:219], off offset:512
	global_load_dwordx2 v[142:143], v[218:219], off offset:1024
	global_load_dwordx2 v[144:145], v[218:219], off offset:1536
	global_load_dwordx2 v[146:147], v[218:219], off offset:2048
	global_load_dwordx2 v[148:149], v[218:219], off offset:2560
	global_load_dwordx2 v[150:151], v[218:219], off offset:3072
	global_load_dwordx2 v[152:153], v[218:219], off offset:3584
	s_add_u32 s56, s56, 2
	s_cmp_le_u32 s56, s60
	s_cbranch_scc1 .Lamoba_loop
	s_nop 15
	s_waitcnt vmcnt(0)
	s_mov_b64 s[58:59], 0
	s_branch .LBB0_933
